# prep-phase mod GEMV loop rewritten (batched loads, DPP row broadcast of silu); inproj/merge tile order 4 M-tiles per group; sample attention loop rescheduled; ssmC recurrence LDS prefetch; out epilogu
# speedup vs baseline: 1.0425x; 1.0425x over previous
; __device__ void phase_out(const Params& p, int l, char* lds) {
;     ...
;     float xo[4][4][4];
; #pragma unroll
;     for (int m = 0; m < 4; ++m) {
;       const int R0 = mt * 128 + wr * 64 + m * 16 + fq * 4;
; #pragma unroll
;       for (int j = 0; j < 4; ++j) {
;         const float* xr = xin_row(p, l, R0 + j) + nt * 128 + wc * 64 + fr;
; #pragma unroll
;         for (int n = 0; n < 4; ++n) xo[m][n][j] = xr[n * 16];
;       }
;     }
; #pragma unroll
;     for (int m = 0; m < 4; ++m) {
;       const int R0 = mt * 128 + wr * 64 + m * 16 + fq * 4;
;       const float* gate = ((float*)(p.ws + WS_mod)) + ((size_t)l * 24 + batch_of(R0)) * 3072 + 2048;
; #pragma unroll
;       for (int n = 0; n < 4; ++n) {
;         const int C = nt * 128 + wc * 64 + n * 16 + fr;
;         const float gv = gate[C];
; #pragma unroll
;         for (int j = 0; j < 4; ++j) p.out[(size_t)(R0 + j) * 1024 + C] = xo[m][n][j] + gv * acc[m][n][j];
.LBB0_33:
	v_lshlrev_b64 v[66:67], 12, v[70:71]
	v_lshl_add_u64 v[66:67], v[72:73], 0, v[66:67]
	v_lshl_add_u64 v[66:67], s[54:55], 2, v[66:67]
	v_lshl_add_u64 v[66:67], v[66:67], 0, v[0:1]
	v_mov_b32_e32 v69, v1
	v_lshl_add_u64 v[66:67], v[66:67], 0, v[68:69]
	v_add_u32_e32 v152, s4, v103
	global_load_dword v134, v[66:67], off
	global_load_dword v130, v[66:67], off offset:64
	global_load_dword v117, v[66:67], off offset:128
	global_load_dword v0, v[66:67], off offset:192
	v_add_u32_e32 v66, 0xffff0000, v152
	v_or_b32_e32 v68, v152, v105
	v_lshrrev_b32_e32 v66, 5, v66
	v_ashrrev_i32_e32 v151, 13, v152
	v_cmp_gt_i32_e32 vcc, s81, v68
	v_add_u32_e32 v66, 8, v66
	v_mov_b64_e32 v[70:71], s[36:37]
	v_cndmask_b32_e32 v66, v66, v151, vcc
	v_ashrrev_i32_e32 v67, 31, v66
	v_lshl_add_u64 v[66:67], s[62:63], 0, v[66:67]
	v_mad_u64_u32 v[72:73], s[0:1], v66, s88, v[70:71]
	v_mov_b32_e32 v66, v73
	v_or_b32_e32 v76, s54, v111
	v_mad_u64_u32 v[66:67], s[0:1], v67, s88, v[66:67]
	v_mov_b32_e32 v73, v66
	s_mov_b64 s[2:3], 0x1f82000
	v_ashrrev_i32_e32 v223, 31, v76
	v_mov_b32_e32 v222, v76
	v_lshlrev_b64 v[214:215], 2, v[222:223]
	v_or_b32_e32 v222, 16, v76
	v_ashrrev_i32_e32 v223, 31, v222
	v_lshlrev_b64 v[216:217], 2, v[222:223]
	v_or_b32_e32 v222, 32, v76
	v_ashrrev_i32_e32 v223, 31, v222
	v_lshlrev_b64 v[218:219], 2, v[222:223]
	v_or_b32_e32 v222, 48, v76
	v_ashrrev_i32_e32 v223, 31, v222
	v_lshlrev_b64 v[220:221], 2, v[222:223]
	v_add_u32_e32 v224, 0xffff0000, v152
	v_mov_b32_e32 v226, v68
	v_lshrrev_b32_e32 v224, 5, v224
	v_cmp_gt_i32_e32 vcc, s81, v226
	v_add_u32_e32 v224, 8, v224
	s_nop 1
	v_cndmask_b32_e32 v224, v224, v151, vcc
	v_ashrrev_i32_e32 v225, 31, v224
	v_lshl_add_u64 v[224:225], s[62:63], 0, v[224:225]
	v_mad_u64_u32 v[226:227], s[0:1], v224, s88, v[70:71]
	v_mov_b32_e32 v224, v227
	v_mad_u64_u32 v[224:225], s[0:1], v225, s88, v[224:225]
	v_mov_b32_e32 v227, v224
	v_lshl_add_u64 v[226:227], v[226:227], 0, s[2:3]
	v_lshl_add_u64 v[228:229], v[226:227], 0, v[214:215]
	global_load_dword v198, v[228:229], off
	v_lshl_add_u64 v[228:229], v[226:227], 0, v[216:217]
	global_load_dword v199, v[228:229], off
	v_lshl_add_u64 v[228:229], v[226:227], 0, v[218:219]
	global_load_dword v200, v[228:229], off
	v_lshl_add_u64 v[228:229], v[226:227], 0, v[220:221]
	global_load_dword v201, v[228:229], off
	v_add_u32_e32 v224, 0xffff0010, v152
	v_or_b32_e32 v226, 16, v68
	v_lshrrev_b32_e32 v224, 5, v224
	v_cmp_gt_i32_e32 vcc, s81, v226
	v_add_u32_e32 v224, 8, v224
	s_nop 1
	v_cndmask_b32_e32 v224, v224, v151, vcc
	v_ashrrev_i32_e32 v225, 31, v224
	v_lshl_add_u64 v[224:225], s[62:63], 0, v[224:225]
	v_mad_u64_u32 v[226:227], s[0:1], v224, s88, v[70:71]
	v_mov_b32_e32 v224, v227
	v_mad_u64_u32 v[224:225], s[0:1], v225, s88, v[224:225]
	v_mov_b32_e32 v227, v224
	v_lshl_add_u64 v[226:227], v[226:227], 0, s[2:3]
	v_lshl_add_u64 v[228:229], v[226:227], 0, v[214:215]
	global_load_dword v202, v[228:229], off
	v_lshl_add_u64 v[228:229], v[226:227], 0, v[216:217]
	global_load_dword v203, v[228:229], off
	v_lshl_add_u64 v[228:229], v[226:227], 0, v[218:219]
	global_load_dword v204, v[228:229], off
	v_lshl_add_u64 v[228:229], v[226:227], 0, v[220:221]
	global_load_dword v205, v[228:229], off
	v_add_u32_e32 v224, 0xffff0020, v152
	v_or_b32_e32 v226, 32, v68
	v_lshrrev_b32_e32 v224, 5, v224
	v_cmp_gt_i32_e32 vcc, s81, v226
	v_add_u32_e32 v224, 8, v224
	s_nop 1
	v_cndmask_b32_e32 v224, v224, v151, vcc
	v_ashrrev_i32_e32 v225, 31, v224
	v_lshl_add_u64 v[224:225], s[62:63], 0, v[224:225]
	v_mad_u64_u32 v[226:227], s[0:1], v224, s88, v[70:71]
	v_mov_b32_e32 v224, v227
	v_mad_u64_u32 v[224:225], s[0:1], v225, s88, v[224:225]
	v_mov_b32_e32 v227, v224
	v_lshl_add_u64 v[226:227], v[226:227], 0, s[2:3]
	v_lshl_add_u64 v[228:229], v[226:227], 0, v[214:215]
	global_load_dword v206, v[228:229], off
	v_lshl_add_u64 v[228:229], v[226:227], 0, v[216:217]
	global_load_dword v207, v[228:229], off
	v_lshl_add_u64 v[228:229], v[226:227], 0, v[218:219]
	global_load_dword v208, v[228:229], off
	v_lshl_add_u64 v[228:229], v[226:227], 0, v[220:221]
	global_load_dword v209, v[228:229], off
	v_add_u32_e32 v224, 0xffff0030, v152
	v_or_b32_e32 v226, 48, v68
	v_lshrrev_b32_e32 v224, 5, v224
	v_cmp_gt_i32_e32 vcc, s81, v226
	v_add_u32_e32 v224, 8, v224
	s_nop 1
	v_cndmask_b32_e32 v224, v224, v151, vcc
	v_ashrrev_i32_e32 v225, 31, v224
	v_lshl_add_u64 v[224:225], s[62:63], 0, v[224:225]
	v_mad_u64_u32 v[226:227], s[0:1], v224, s88, v[70:71]
	v_mov_b32_e32 v224, v227
	v_mad_u64_u32 v[224:225], s[0:1], v225, s88, v[224:225]
	v_mov_b32_e32 v227, v224
	v_lshl_add_u64 v[226:227], v[226:227], 0, s[2:3]
	v_lshl_add_u64 v[228:229], v[226:227], 0, v[214:215]
	global_load_dword v210, v[228:229], off
	v_lshl_add_u64 v[228:229], v[226:227], 0, v[216:217]
	global_load_dword v211, v[228:229], off
	v_lshl_add_u64 v[228:229], v[226:227], 0, v[218:219]
	global_load_dword v212, v[228:229], off
	v_lshl_add_u64 v[228:229], v[226:227], 0, v[220:221]
	global_load_dword v213, v[228:229], off
	v_ashrrev_i32_e32 v77, 31, v76
	v_lshl_add_u64 v[82:83], v[72:73], 0, s[2:3]
	v_lshlrev_b64 v[72:73], 2, v[76:77]
	v_lshl_add_u64 v[66:67], v[82:83], 0, v[72:73]
	s_nop 0
	v_readlane_b32 s0, v234, 36
	v_readlane_b32 s1, v234, 37
	v_ashrrev_i32_e32 v69, 31, v68
	v_lshlrev_b64 v[74:75], 12, v[68:69]
	v_lshl_add_u64 v[66:67], s[0:1], 0, v[72:73]
	v_lshl_add_u64 v[74:75], v[66:67], 0, v[74:75]
	s_waitcnt vmcnt(0) lgkmcnt(0)
; __device__ void phase_out(const Params& p, int l, char* lds) {
;     ...
; #pragma unroll
;     for (int m = 0; m < 4; ++m) {
;       const int R0 = mt * 128 + wr * 64 + m * 16 + fq * 4;
;       const float* gate = ((float*)(p.ws + WS_mod)) + ((size_t)l * 24 + batch_of(R0)) * 3072 + 2048;
; #pragma unroll
;       for (int n = 0; n < 4; ++n) {
;         const int C = nt * 128 + wc * 64 + n * 16 + fr;
;         const float gv = gate[C];
; #pragma unroll
;         for (int j = 0; j < 4; ++j) p.out[(size_t)(R0 + j) * 1024 + C] = xo[m][n][j] + gv * acc[m][n][j];
	v_fmac_f32_e32 v78, v62, v198
	v_or_b32_e32 v62, 1, v68
	v_fmac_f32_e32 v80, v63, v198
	v_ashrrev_i32_e32 v63, 31, v62
	v_lshlrev_b64 v[62:63], 12, v[62:63]
	global_store_dword v[74:75], v78, off
	v_lshl_add_u64 v[78:79], v[66:67], 0, v[62:63]
	v_or_b32_e32 v62, 2, v68
	v_ashrrev_i32_e32 v63, 31, v62
	v_lshlrev_b64 v[62:63], 12, v[62:63]
	global_store_dword v[78:79], v80, off
	v_lshl_add_u64 v[80:81], v[66:67], 0, v[62:63]
	v_or_b32_e32 v62, 3, v68
	v_ashrrev_i32_e32 v63, 31, v62
	v_lshlrev_b64 v[62:63], 12, v[62:63]
	v_fmac_f32_e32 v153, v64, v198
	v_fmac_f32_e32 v184, v65, v198
	v_lshl_add_u64 v[64:65], v[66:67], 0, v[62:63]
	v_or_b32_e32 v62, 16, v76
	v_ashrrev_i32_e32 v63, 31, v62
	v_lshlrev_b64 v[62:63], 2, v[62:63]
	global_store_dword v[80:81], v153, off
	global_store_dword v[64:65], v184, off
	v_lshl_add_u64 v[184:185], v[82:83], 0, v[62:63]
	s_nop 0
	s_nop 0
	v_fmac_f32_e32 v122, v58, v199
	v_or_b32_e32 v58, 32, v76
	v_fmac_f32_e32 v136, v59, v199
	v_ashrrev_i32_e32 v59, 31, v58
	v_fmac_f32_e32 v145, v60, v199
	v_fmac_f32_e32 v150, v61, v199
	v_lshlrev_b64 v[58:59], 2, v[58:59]
	global_store_dword v[74:75], v122, off offset:64
	global_store_dword v[78:79], v136, off offset:64
	global_store_dword v[80:81], v145, off offset:64
	global_store_dword v[64:65], v150, off offset:64
	v_lshl_add_u64 v[60:61], v[82:83], 0, v[58:59]
	s_nop 0
	s_nop 0
	v_fmac_f32_e32 v106, v54, v200
	v_or_b32_e32 v54, 48, v76
	v_fmac_f32_e32 v124, v55, v200
	v_ashrrev_i32_e32 v55, 31, v54
	v_fmac_f32_e32 v138, v56, v200
	v_fmac_f32_e32 v147, v57, v200
	v_lshlrev_b64 v[54:55], 2, v[54:55]
	global_store_dword v[74:75], v106, off offset:128
	global_store_dword v[78:79], v124, off offset:128
	global_store_dword v[80:81], v138, off offset:128
	global_store_dword v[64:65], v147, off offset:128
	v_lshl_add_u64 v[56:57], v[82:83], 0, v[54:55]
	s_nop 0
	s_nop 0
	v_fmac_f32_e32 v94, v50, v201
	v_add_u32_e32 v50, 0xffff0010, v152
	v_fmac_f32_e32 v126, v52, v201
	v_or_b32_e32 v52, 16, v68
	v_lshrrev_b32_e32 v50, 5, v50
	v_cmp_gt_i32_e32 vcc, s81, v52
	v_add_u32_e32 v50, 8, v50
	v_fmac_f32_e32 v108, v51, v201
	v_cndmask_b32_e32 v50, v50, v151, vcc
	v_ashrrev_i32_e32 v51, 31, v50
	v_lshl_add_u64 v[50:51], s[62:63], 0, v[50:51]
	v_fmac_f32_e32 v139, v53, v201
	v_mad_u64_u32 v[56:57], s[0:1], v50, s88, v[70:71]
	v_mov_b32_e32 v50, v57
	v_mad_u64_u32 v[50:51], s[0:1], v51, s88, v[50:51]
	v_mov_b32_e32 v57, v50
	v_lshl_add_u64 v[50:51], v[56:57], 0, s[2:3]
	global_store_dword v[74:75], v94, off offset:192
	global_store_dword v[78:79], v108, off offset:192
	global_store_dword v[80:81], v126, off offset:192
	global_store_dword v[64:65], v139, off offset:192
	v_lshl_add_u64 v[56:57], v[50:51], 0, v[72:73]
	s_nop 0
	v_or_b32_e32 v56, 18, v68
	v_ashrrev_i32_e32 v53, 31, v52
	v_ashrrev_i32_e32 v57, 31, v56
	v_lshlrev_b64 v[52:53], 12, v[52:53]
	v_lshlrev_b64 v[56:57], 12, v[56:57]
	v_lshl_add_u64 v[52:53], v[66:67], 0, v[52:53]
	v_lshl_add_u64 v[56:57], v[66:67], 0, v[56:57]
	s_nop 0
	v_fmac_f32_e32 v135, v46, v202
	v_or_b32_e32 v46, 17, v68
	v_fmac_f32_e32 v148, v48, v202
	v_or_b32_e32 v48, 19, v68
	v_fmac_f32_e32 v143, v47, v202
	v_ashrrev_i32_e32 v47, 31, v46
	v_fmac_f32_e32 v149, v49, v202
	v_ashrrev_i32_e32 v49, 31, v48
	v_lshlrev_b64 v[46:47], 12, v[46:47]
	v_lshlrev_b64 v[48:49], 12, v[48:49]
	v_lshl_add_u64 v[46:47], v[66:67], 0, v[46:47]
	v_lshl_add_u64 v[48:49], v[66:67], 0, v[48:49]
	global_store_dword v[52:53], v135, off
	global_store_dword v[46:47], v143, off
	global_store_dword v[56:57], v148, off
	global_store_dword v[48:49], v149, off
	v_lshl_add_u64 v[60:61], v[50:51], 0, v[62:63]
	s_nop 0
	s_nop 0
	v_fmac_f32_e32 v107, v42, v203
	v_fmac_f32_e32 v123, v43, v203
	v_fmac_f32_e32 v137, v44, v203
	v_fmac_f32_e32 v146, v45, v203
	global_store_dword v[52:53], v107, off offset:64
	global_store_dword v[46:47], v123, off offset:64
	global_store_dword v[56:57], v137, off offset:64
	global_store_dword v[48:49], v146, off offset:64
	v_lshl_add_u64 v[42:43], v[50:51], 0, v[58:59]
	s_nop 0
	s_nop 0
	v_fmac_f32_e32 v95, v38, v204
	v_fmac_f32_e32 v109, v39, v204
	v_fmac_f32_e32 v127, v40, v204
	v_fmac_f32_e32 v140, v41, v204
	global_store_dword v[52:53], v95, off offset:128
	global_store_dword v[46:47], v109, off offset:128
	global_store_dword v[56:57], v127, off offset:128
	global_store_dword v[48:49], v140, off offset:128
	v_lshl_add_u64 v[38:39], v[50:51], 0, v[54:55]
	s_nop 0
	s_nop 0
	v_fmac_f32_e32 v88, v34, v205
	v_add_u32_e32 v34, 0xffff0020, v152
	v_fmac_f32_e32 v114, v36, v205
	v_or_b32_e32 v36, 32, v68
	v_lshrrev_b32_e32 v34, 5, v34
	v_cmp_gt_i32_e32 vcc, s81, v36
	v_add_u32_e32 v34, 8, v34
	v_fmac_f32_e32 v97, v35, v205
	v_cndmask_b32_e32 v34, v34, v151, vcc
	v_ashrrev_i32_e32 v35, 31, v34
	v_lshl_add_u64 v[34:35], s[62:63], 0, v[34:35]
	v_fmac_f32_e32 v129, v37, v205
	v_mad_u64_u32 v[38:39], s[0:1], v34, s88, v[70:71]
	v_mov_b32_e32 v34, v39
	v_mad_u64_u32 v[34:35], s[0:1], v35, s88, v[34:35]
; __device__ void phase_out(const Params& p, int l, char* lds) {
;     ...
; #pragma unroll
;     for (int m = 0; m < 4; ++m) {
;       const int R0 = mt * 128 + wr * 64 + m * 16 + fq * 4;
;       const float* gate = ((float*)(p.ws + WS_mod)) + ((size_t)l * 24 + batch_of(R0)) * 3072 + 2048;
; #pragma unroll
;       for (int n = 0; n < 4; ++n) {
;         const int C = nt * 128 + wc * 64 + n * 16 + fr;
;         const float gv = gate[C];
; #pragma unroll
;         for (int j = 0; j < 4; ++j) p.out[(size_t)(R0 + j) * 1024 + C] = xo[m][n][j] + gv * acc[m][n][j];
	v_mov_b32_e32 v39, v34
	v_lshl_add_u64 v[34:35], v[38:39], 0, s[2:3]
	global_store_dword v[52:53], v88, off offset:192
	global_store_dword v[46:47], v97, off offset:192
	global_store_dword v[56:57], v114, off offset:192
	global_store_dword v[48:49], v129, off offset:192
	v_lshl_add_u64 v[38:39], v[34:35], 0, v[72:73]
	s_nop 0
	v_or_b32_e32 v38, 34, v68
	v_ashrrev_i32_e32 v37, 31, v36
	v_ashrrev_i32_e32 v39, 31, v38
	v_lshlrev_b64 v[36:37], 12, v[36:37]
	v_lshlrev_b64 v[38:39], 12, v[38:39]
	v_lshl_add_u64 v[36:37], v[66:67], 0, v[36:37]
	v_lshl_add_u64 v[38:39], v[66:67], 0, v[38:39]
	s_nop 0
	v_fmac_f32_e32 v125, v30, v206
	v_or_b32_e32 v30, 33, v68
	v_fmac_f32_e32 v142, v32, v206
	v_or_b32_e32 v32, 35, v68
	v_fmac_f32_e32 v133, v31, v206
	v_ashrrev_i32_e32 v31, 31, v30
	v_fmac_f32_e32 v144, v33, v206
	v_ashrrev_i32_e32 v33, 31, v32
	v_lshlrev_b64 v[30:31], 12, v[30:31]
	v_lshlrev_b64 v[32:33], 12, v[32:33]
	v_lshl_add_u64 v[30:31], v[66:67], 0, v[30:31]
	v_lshl_add_u64 v[32:33], v[66:67], 0, v[32:33]
	global_store_dword v[36:37], v125, off
	global_store_dword v[30:31], v133, off
	global_store_dword v[38:39], v142, off
	global_store_dword v[32:33], v144, off
	v_lshl_add_u64 v[40:41], v[34:35], 0, v[62:63]
	s_nop 0
	s_nop 0
	v_fmac_f32_e32 v96, v26, v207
	v_fmac_f32_e32 v112, v27, v207
	v_fmac_f32_e32 v128, v28, v207
	v_fmac_f32_e32 v141, v29, v207
	global_store_dword v[36:37], v96, off offset:64
	global_store_dword v[30:31], v112, off offset:64
	global_store_dword v[38:39], v128, off offset:64
	global_store_dword v[32:33], v141, off offset:64
	v_lshl_add_u64 v[26:27], v[34:35], 0, v[58:59]
	s_nop 0
	s_nop 0
	v_fmac_f32_e32 v89, v22, v208
	v_fmac_f32_e32 v98, v23, v208
	v_fmac_f32_e32 v115, v24, v208
	v_fmac_f32_e32 v131, v25, v208
	global_store_dword v[36:37], v89, off offset:128
	global_store_dword v[30:31], v98, off offset:128
	global_store_dword v[38:39], v115, off offset:128
	global_store_dword v[32:33], v131, off offset:128
	v_lshl_add_u64 v[22:23], v[34:35], 0, v[54:55]
	s_nop 0
	s_nop 0
	v_fmac_f32_e32 v85, v18, v209
	v_add_u32_e32 v18, 0xffff0030, v152
	v_fmac_f32_e32 v100, v20, v209
	v_or_b32_e32 v20, 48, v68
	v_lshrrev_b32_e32 v18, 5, v18
	v_cmp_gt_i32_e32 vcc, s81, v20
	v_add_u32_e32 v18, 8, v18
	v_fmac_f32_e32 v91, v19, v209
	v_cndmask_b32_e32 v18, v18, v151, vcc
	v_ashrrev_i32_e32 v19, 31, v18
	v_lshl_add_u64 v[18:19], s[62:63], 0, v[18:19]
	v_fmac_f32_e32 v118, v21, v209
	v_mad_u64_u32 v[22:23], s[0:1], v18, s88, v[70:71]
	v_mov_b32_e32 v18, v23
	v_mad_u64_u32 v[18:19], s[0:1], v19, s88, v[18:19]
	v_mov_b32_e32 v23, v18
	v_lshl_add_u64 v[18:19], v[22:23], 0, s[2:3]
	global_store_dword v[36:37], v85, off offset:192
	global_store_dword v[30:31], v91, off offset:192
	global_store_dword v[38:39], v100, off offset:192
	global_store_dword v[32:33], v118, off offset:192
	v_lshl_add_u64 v[22:23], v[18:19], 0, v[72:73]
	s_nop 0
	v_or_b32_e32 v22, 50, v68
	v_ashrrev_i32_e32 v21, 31, v20
	v_ashrrev_i32_e32 v23, 31, v22
	v_lshlrev_b64 v[20:21], 12, v[20:21]
	v_lshlrev_b64 v[22:23], 12, v[22:23]
	v_lshl_add_u64 v[20:21], v[66:67], 0, v[20:21]
	v_lshl_add_u64 v[22:23], v[66:67], 0, v[22:23]
	s_mov_b64 s[0:1], 0
	s_nop 0
	v_fmac_f32_e32 v113, v14, v210
	v_or_b32_e32 v14, 49, v68
	v_fmac_f32_e32 v132, v16, v210
	v_or_b32_e32 v16, 51, v68
	v_fmac_f32_e32 v119, v15, v210
	v_ashrrev_i32_e32 v15, 31, v14
	v_fmac_f32_e32 v134, v17, v210
	v_ashrrev_i32_e32 v17, 31, v16
	v_lshlrev_b64 v[14:15], 12, v[14:15]
	v_lshlrev_b64 v[16:17], 12, v[16:17]
	v_lshl_add_u64 v[14:15], v[66:67], 0, v[14:15]
	v_lshl_add_u64 v[16:17], v[66:67], 0, v[16:17]
	global_store_dword v[20:21], v113, off
	global_store_dword v[14:15], v119, off
	global_store_dword v[22:23], v132, off
	global_store_dword v[16:17], v134, off
	v_lshl_add_u64 v[24:25], v[18:19], 0, v[62:63]
	s_nop 0
	s_nop 0
	v_fmac_f32_e32 v90, v10, v211
	v_fmac_f32_e32 v99, v11, v211
	v_fmac_f32_e32 v116, v12, v211
	v_fmac_f32_e32 v130, v13, v211
	global_store_dword v[20:21], v90, off offset:64
	global_store_dword v[14:15], v99, off offset:64
	global_store_dword v[22:23], v116, off offset:64
	global_store_dword v[16:17], v130, off offset:64
	v_lshl_add_u64 v[10:11], v[18:19], 0, v[58:59]
	s_nop 0
	s_nop 0
	v_fmac_f32_e32 v86, v6, v212
	v_fmac_f32_e32 v92, v7, v212
	v_fmac_f32_e32 v101, v8, v212
	v_fmac_f32_e32 v117, v9, v212
	global_store_dword v[20:21], v86, off offset:128
	global_store_dword v[14:15], v92, off offset:128
	global_store_dword v[22:23], v101, off offset:128
	global_store_dword v[16:17], v117, off offset:128
	v_lshl_add_u64 v[6:7], v[18:19], 0, v[54:55]
	s_nop 0
	s_nop 0
	v_fmac_f32_e32 v84, v2, v213
	v_fmac_f32_e32 v87, v3, v213
	v_fmac_f32_e32 v93, v4, v213
	v_fmac_f32_e32 v0, v5, v213
	global_store_dword v[20:21], v84, off offset:192
	global_store_dword v[14:15], v87, off offset:192
	global_store_dword v[22:23], v93, off offset:192
	global_store_dword v[16:17], v0, off offset:192

;   DI bool next(int& mt, int& nt) {
;     for (;;) {
;       const int s = j + nb * k; ++k;
;       const int g = s / (2 * NN), r = s - g * (2 * NN);
;       if (g * 2 >= cnt) return false;
;       const int i = g * 2 + (r & 1);
;       if (i >= cnt) continue;
;       mt = x + 8 * i; nt = r >> 1; return true;
;     }
.LBB0_175:
	v_readlane_b32 s2, v236, 9
	s_mul_i32 s4, s84, s2
	v_readlane_b32 s2, v236, 20
	s_add_i32 s4, s4, s2
	s_lshr_b32 s2, s4, 4
	s_and_b32 s2, s2, 0x7fffffc
	v_readlane_b32 s6, v236, 10
	s_cmp_ge_u32 s2, s6
	v_readlane_b32 s3, v236, 21
	s_cbranch_scc1 .LBB0_179
	s_and_b32 s3, s4, 3
	s_or_b32 s5, s2, s3
	s_cmp_ge_u32 s5, s6
	s_mov_b64 s[2:3], 0
	s_cbranch_scc1 .LBB0_178
	s_lshl_b32 s0, s5, 3
	s_or_b32 s66, s0, s17
	s_bfe_u32 s68, s4, 0x40002
	s_mov_b64 s[0:1], -1
	s_branch .LBB0_180

; DI uint32_t pack2(float a, float b) { return (uint32_t)f2bf(a) | ((uint32_t)f2bf(b) << 16); }
; DI f32x4 mfma16(bf16x8 a, bf16x8 b, f32x4 c) { return __builtin_amdgcn_mfma_f32_16x16x32_bf16(a, b, c, 0, 0, 0); }
; DI void ssm_unit(const Params& p, int l, int g, int row0, int T, float& hr, float& hi, bool write_y, u16* tile) {
;     ...
; #pragma unroll
;   for (int nt = 0; nt < 4; ++nt) {
;     if (nt >= ntile) break;
;     const bf16x8 bu = bu4[nt];
; #pragma unroll
;     for (int mt = 0; mt < 8; ++mt) {
;       const f32x4 a = mfma16(am[mt], bu, f32x4{0.f, 0.f, 0.f, 0.f});
;       uint2 o; o.x = pack2(a[0], a[1]); o.y = pack2(a[2], a[3]);
;       *reinterpret_cast<uint2*>(tile + (nt * 16 + fr) * 136 + mt * 16 + fq * 4) = o;
;     }
;   }
.LBB0_253:
	s_or_b64 exec, exec, s[54:55]
	v_mul_u32_u24_e32 v61, 0x88, v66
	v_lshlrev_b32_e32 v74, 1, v61
	v_lshlrev_b32_e32 v60, 2, v69
	v_add3_u32 v61, v64, v68, v74
	s_waitcnt vmcnt(0) lgkmcnt(0)
	v_mfma_f32_16x16x32_bf16 v[68:71], v[6:9], v[46:49], 0
	s_nop 7
	v_and_b32_sdwa v62, v70, v157 dst_sel:DWORD dst_unused:UNUSED_PAD src0_sel:WORD_1 src1_sel:DWORD
	v_and_b32_sdwa v63, v68, v157 dst_sel:DWORD dst_unused:UNUSED_PAD src0_sel:WORD_1 src1_sel:DWORD
	v_add3_u32 v68, v68, v63, s94
	v_add3_u32 v62, v70, v62, s94
	v_and_b32_sdwa v63, v71, v157 dst_sel:DWORD dst_unused:UNUSED_PAD src0_sel:WORD_1 src1_sel:DWORD
	v_and_b32_sdwa v70, v69, v157 dst_sel:DWORD dst_unused:UNUSED_PAD src0_sel:WORD_1 src1_sel:DWORD
	v_add3_u32 v63, v71, v63, s94
	v_add3_u32 v69, v69, v70, s94
	v_and_b32_e32 v63, 0xffff0000, v63
	v_and_b32_e32 v69, 0xffff0000, v69
	v_or_b32_sdwa v63, v63, v62 dst_sel:DWORD dst_unused:UNUSED_PAD src0_sel:DWORD src1_sel:WORD_1
	v_or_b32_sdwa v62, v69, v68 dst_sel:DWORD dst_unused:UNUSED_PAD src0_sel:DWORD src1_sel:WORD_1
	v_mfma_f32_16x16x32_bf16 v[68:71], v[2:5], v[46:49], 0
	s_nop 7
	v_and_b32_sdwa v72, v70, v157 dst_sel:DWORD dst_unused:UNUSED_PAD src0_sel:WORD_1 src1_sel:DWORD
	v_and_b32_sdwa v73, v68, v157 dst_sel:DWORD dst_unused:UNUSED_PAD src0_sel:WORD_1 src1_sel:DWORD
	v_add3_u32 v68, v68, v73, s94
	v_add3_u32 v70, v70, v72, s94
	v_and_b32_sdwa v72, v71, v157 dst_sel:DWORD dst_unused:UNUSED_PAD src0_sel:WORD_1 src1_sel:DWORD
	v_and_b32_sdwa v73, v69, v157 dst_sel:DWORD dst_unused:UNUSED_PAD src0_sel:WORD_1 src1_sel:DWORD
	v_add3_u32 v71, v71, v72, s94
	v_add3_u32 v69, v69, v73, s94
	v_and_b32_e32 v71, 0xffff0000, v71
	v_and_b32_e32 v72, 0xffff0000, v69
	v_or_b32_sdwa v69, v71, v70 dst_sel:DWORD dst_unused:UNUSED_PAD src0_sel:DWORD src1_sel:WORD_1
	v_or_b32_sdwa v68, v72, v68 dst_sel:DWORD dst_unused:UNUSED_PAD src0_sel:DWORD src1_sel:WORD_1
	ds_write2_b64 v61, v[62:63], v[68:69] offset1:4
	v_mfma_f32_16x16x32_bf16 v[68:71], v[14:17], v[46:49], 0
	s_nop 7
	v_and_b32_sdwa v62, v70, v157 dst_sel:DWORD dst_unused:UNUSED_PAD src0_sel:WORD_1 src1_sel:DWORD
	v_and_b32_sdwa v63, v68, v157 dst_sel:DWORD dst_unused:UNUSED_PAD src0_sel:WORD_1 src1_sel:DWORD
	v_add3_u32 v68, v68, v63, s94
	v_add3_u32 v62, v70, v62, s94
	v_and_b32_sdwa v63, v71, v157 dst_sel:DWORD dst_unused:UNUSED_PAD src0_sel:WORD_1 src1_sel:DWORD
	v_and_b32_sdwa v70, v69, v157 dst_sel:DWORD dst_unused:UNUSED_PAD src0_sel:WORD_1 src1_sel:DWORD
	v_add3_u32 v63, v71, v63, s94
	v_add3_u32 v69, v69, v70, s94
	v_and_b32_e32 v63, 0xffff0000, v63
	v_and_b32_e32 v69, 0xffff0000, v69
	v_or_b32_sdwa v63, v63, v62 dst_sel:DWORD dst_unused:UNUSED_PAD src0_sel:DWORD src1_sel:WORD_1
	v_or_b32_sdwa v62, v69, v68 dst_sel:DWORD dst_unused:UNUSED_PAD src0_sel:DWORD src1_sel:WORD_1
	v_mfma_f32_16x16x32_bf16 v[68:71], v[10:13], v[46:49], 0
	s_nop 7
	v_and_b32_sdwa v72, v70, v157 dst_sel:DWORD dst_unused:UNUSED_PAD src0_sel:WORD_1 src1_sel:DWORD
	v_and_b32_sdwa v73, v68, v157 dst_sel:DWORD dst_unused:UNUSED_PAD src0_sel:WORD_1 src1_sel:DWORD
	v_add3_u32 v68, v68, v73, s94
	v_add3_u32 v70, v70, v72, s94
	v_and_b32_sdwa v72, v71, v157 dst_sel:DWORD dst_unused:UNUSED_PAD src0_sel:WORD_1 src1_sel:DWORD
	v_and_b32_sdwa v73, v69, v157 dst_sel:DWORD dst_unused:UNUSED_PAD src0_sel:WORD_1 src1_sel:DWORD
	v_add3_u32 v71, v71, v72, s94
	v_add3_u32 v69, v69, v73, s94
	v_and_b32_e32 v71, 0xffff0000, v71
	v_and_b32_e32 v72, 0xffff0000, v69
	v_or_b32_sdwa v69, v71, v70 dst_sel:DWORD dst_unused:UNUSED_PAD src0_sel:DWORD src1_sel:WORD_1
	v_or_b32_sdwa v68, v72, v68 dst_sel:DWORD dst_unused:UNUSED_PAD src0_sel:DWORD src1_sel:WORD_1
	ds_write2_b64 v61, v[62:63], v[68:69] offset0:8 offset1:12
	v_mfma_f32_16x16x32_bf16 v[68:71], v[22:25], v[46:49], 0
	s_nop 7
	v_and_b32_sdwa v62, v70, v157 dst_sel:DWORD dst_unused:UNUSED_PAD src0_sel:WORD_1 src1_sel:DWORD
	v_and_b32_sdwa v63, v68, v157 dst_sel:DWORD dst_unused:UNUSED_PAD src0_sel:WORD_1 src1_sel:DWORD
	v_add3_u32 v68, v68, v63, s94
	v_add3_u32 v62, v70, v62, s94
	v_and_b32_sdwa v63, v71, v157 dst_sel:DWORD dst_unused:UNUSED_PAD src0_sel:WORD_1 src1_sel:DWORD
	v_and_b32_sdwa v70, v69, v157 dst_sel:DWORD dst_unused:UNUSED_PAD src0_sel:WORD_1 src1_sel:DWORD
	v_add3_u32 v63, v71, v63, s94
	v_add3_u32 v69, v69, v70, s94
	v_and_b32_e32 v63, 0xffff0000, v63
	v_and_b32_e32 v69, 0xffff0000, v69
	v_or_b32_sdwa v63, v63, v62 dst_sel:DWORD dst_unused:UNUSED_PAD src0_sel:DWORD src1_sel:WORD_1
	v_or_b32_sdwa v62, v69, v68 dst_sel:DWORD dst_unused:UNUSED_PAD src0_sel:DWORD src1_sel:WORD_1
	v_mfma_f32_16x16x32_bf16 v[68:71], v[18:21], v[46:49], 0
	s_nop 7
	v_and_b32_sdwa v72, v70, v157 dst_sel:DWORD dst_unused:UNUSED_PAD src0_sel:WORD_1 src1_sel:DWORD
	v_and_b32_sdwa v73, v68, v157 dst_sel:DWORD dst_unused:UNUSED_PAD src0_sel:WORD_1 src1_sel:DWORD
	v_add3_u32 v68, v68, v73, s94
	v_add3_u32 v70, v70, v72, s94
	v_and_b32_sdwa v72, v71, v157 dst_sel:DWORD dst_unused:UNUSED_PAD src0_sel:WORD_1 src1_sel:DWORD
	v_and_b32_sdwa v73, v69, v157 dst_sel:DWORD dst_unused:UNUSED_PAD src0_sel:WORD_1 src1_sel:DWORD
	v_add3_u32 v71, v71, v72, s94
	v_add3_u32 v69, v69, v73, s94
	v_and_b32_e32 v71, 0xffff0000, v71
	v_and_b32_e32 v72, 0xffff0000, v69
	v_or_b32_sdwa v69, v71, v70 dst_sel:DWORD dst_unused:UNUSED_PAD src0_sel:DWORD src1_sel:WORD_1
	v_or_b32_sdwa v68, v72, v68 dst_sel:DWORD dst_unused:UNUSED_PAD src0_sel:DWORD src1_sel:WORD_1
	ds_write2_b64 v61, v[62:63], v[68:69] offset0:16 offset1:20
	v_mfma_f32_16x16x32_bf16 v[68:71], v[30:33], v[46:49], 0
	v_mfma_f32_16x16x32_bf16 v[46:49], v[26:29], v[46:49], 0
	s_nop 6
	v_and_b32_sdwa v62, v70, v157 dst_sel:DWORD dst_unused:UNUSED_PAD src0_sel:WORD_1 src1_sel:DWORD
; DI uint32_t pack2(float a, float b) { return (uint32_t)f2bf(a) | ((uint32_t)f2bf(b) << 16); }
; DI f32x4 mfma16(bf16x8 a, bf16x8 b, f32x4 c) { return __builtin_amdgcn_mfma_f32_16x16x32_bf16(a, b, c, 0, 0, 0); }
; DI void ssm_unit(const Params& p, int l, int g, int row0, int T, float& hr, float& hi, bool write_y, u16* tile) {
;     ...
; #pragma unroll
;   for (int nt = 0; nt < 4; ++nt) {
;     if (nt >= ntile) break;
;     const bf16x8 bu = bu4[nt];
; #pragma unroll
;     for (int mt = 0; mt < 8; ++mt) {
;       const f32x4 a = mfma16(am[mt], bu, f32x4{0.f, 0.f, 0.f, 0.f});
;       uint2 o; o.x = pack2(a[0], a[1]); o.y = pack2(a[2], a[3]);
;       *reinterpret_cast<uint2*>(tile + (nt * 16 + fr) * 136 + mt * 16 + fq * 4) = o;
;     }
;   }
	v_and_b32_sdwa v63, v68, v157 dst_sel:DWORD dst_unused:UNUSED_PAD src0_sel:WORD_1 src1_sel:DWORD
	v_add3_u32 v68, v68, v63, s94
	v_add3_u32 v62, v70, v62, s94
	v_and_b32_sdwa v63, v71, v157 dst_sel:DWORD dst_unused:UNUSED_PAD src0_sel:WORD_1 src1_sel:DWORD
	v_and_b32_sdwa v70, v69, v157 dst_sel:DWORD dst_unused:UNUSED_PAD src0_sel:WORD_1 src1_sel:DWORD
	v_add3_u32 v63, v71, v63, s94
	v_add3_u32 v69, v69, v70, s94
	v_and_b32_e32 v63, 0xffff0000, v63
	v_and_b32_e32 v69, 0xffff0000, v69
	v_or_b32_sdwa v63, v63, v62 dst_sel:DWORD dst_unused:UNUSED_PAD src0_sel:DWORD src1_sel:WORD_1
	v_or_b32_sdwa v62, v69, v68 dst_sel:DWORD dst_unused:UNUSED_PAD src0_sel:DWORD src1_sel:WORD_1
	v_and_b32_sdwa v68, v48, v157 dst_sel:DWORD dst_unused:UNUSED_PAD src0_sel:WORD_1 src1_sel:DWORD
	v_and_b32_sdwa v69, v46, v157 dst_sel:DWORD dst_unused:UNUSED_PAD src0_sel:WORD_1 src1_sel:DWORD
	v_add3_u32 v46, v46, v69, s94
	v_add3_u32 v48, v48, v68, s94
	v_and_b32_sdwa v68, v49, v157 dst_sel:DWORD dst_unused:UNUSED_PAD src0_sel:WORD_1 src1_sel:DWORD
	v_and_b32_sdwa v69, v47, v157 dst_sel:DWORD dst_unused:UNUSED_PAD src0_sel:WORD_1 src1_sel:DWORD
	v_add3_u32 v49, v49, v68, s94
	v_add3_u32 v47, v47, v69, s94
	v_and_b32_e32 v49, 0xffff0000, v49
	v_and_b32_e32 v68, 0xffff0000, v47
	v_or_b32_sdwa v47, v49, v48 dst_sel:DWORD dst_unused:UNUSED_PAD src0_sel:DWORD src1_sel:WORD_1
	v_or_b32_sdwa v46, v68, v46 dst_sel:DWORD dst_unused:UNUSED_PAD src0_sel:DWORD src1_sel:WORD_1
	ds_write2_b64 v61, v[62:63], v[46:47] offset0:24 offset1:28
	v_mfma_f32_16x16x32_bf16 v[46:49], v[6:9], v[42:45], 0
	s_nop 7
	v_and_b32_sdwa v62, v48, v157 dst_sel:DWORD dst_unused:UNUSED_PAD src0_sel:WORD_1 src1_sel:DWORD
	v_and_b32_sdwa v63, v46, v157 dst_sel:DWORD dst_unused:UNUSED_PAD src0_sel:WORD_1 src1_sel:DWORD
	v_add3_u32 v46, v46, v63, s94
	v_add3_u32 v48, v48, v62, s94
	v_and_b32_sdwa v62, v49, v157 dst_sel:DWORD dst_unused:UNUSED_PAD src0_sel:WORD_1 src1_sel:DWORD
	v_and_b32_sdwa v63, v47, v157 dst_sel:DWORD dst_unused:UNUSED_PAD src0_sel:WORD_1 src1_sel:DWORD
	v_add3_u32 v49, v49, v62, s94
	v_add3_u32 v47, v47, v63, s94
	v_and_b32_e32 v49, 0xffff0000, v49
	v_and_b32_e32 v47, 0xffff0000, v47
	v_or_b32_sdwa v63, v49, v48 dst_sel:DWORD dst_unused:UNUSED_PAD src0_sel:DWORD src1_sel:WORD_1
	v_or_b32_sdwa v62, v47, v46 dst_sel:DWORD dst_unused:UNUSED_PAD src0_sel:DWORD src1_sel:WORD_1
	v_mfma_f32_16x16x32_bf16 v[46:49], v[2:5], v[42:45], 0
	s_nop 7
	v_and_b32_sdwa v68, v48, v157 dst_sel:DWORD dst_unused:UNUSED_PAD src0_sel:WORD_1 src1_sel:DWORD
	v_and_b32_sdwa v69, v46, v157 dst_sel:DWORD dst_unused:UNUSED_PAD src0_sel:WORD_1 src1_sel:DWORD
	v_add3_u32 v46, v46, v69, s94
	v_add3_u32 v48, v48, v68, s94
	v_and_b32_sdwa v68, v49, v157 dst_sel:DWORD dst_unused:UNUSED_PAD src0_sel:WORD_1 src1_sel:DWORD
	v_and_b32_sdwa v69, v47, v157 dst_sel:DWORD dst_unused:UNUSED_PAD src0_sel:WORD_1 src1_sel:DWORD
	v_add3_u32 v49, v49, v68, s94
	v_add3_u32 v47, v47, v69, s94
	v_and_b32_e32 v49, 0xffff0000, v49
	v_and_b32_e32 v68, 0xffff0000, v47
	v_or_b32_sdwa v47, v49, v48 dst_sel:DWORD dst_unused:UNUSED_PAD src0_sel:DWORD src1_sel:WORD_1
	v_or_b32_sdwa v46, v68, v46 dst_sel:DWORD dst_unused:UNUSED_PAD src0_sel:DWORD src1_sel:WORD_1
	v_add_u32_e32 v68, 0x1000, v61
	ds_write2_b64 v68, v[62:63], v[46:47] offset0:32 offset1:36
	v_mfma_f32_16x16x32_bf16 v[46:49], v[14:17], v[42:45], 0
	s_nop 7
	v_and_b32_sdwa v62, v48, v157 dst_sel:DWORD dst_unused:UNUSED_PAD src0_sel:WORD_1 src1_sel:DWORD
	v_and_b32_sdwa v63, v46, v157 dst_sel:DWORD dst_unused:UNUSED_PAD src0_sel:WORD_1 src1_sel:DWORD
	v_add3_u32 v46, v46, v63, s94
	v_add3_u32 v48, v48, v62, s94
	v_and_b32_sdwa v62, v49, v157 dst_sel:DWORD dst_unused:UNUSED_PAD src0_sel:WORD_1 src1_sel:DWORD
	v_and_b32_sdwa v63, v47, v157 dst_sel:DWORD dst_unused:UNUSED_PAD src0_sel:WORD_1 src1_sel:DWORD
	v_add3_u32 v49, v49, v62, s94
	v_add3_u32 v47, v47, v63, s94
	v_and_b32_e32 v49, 0xffff0000, v49
	v_and_b32_e32 v47, 0xffff0000, v47
	v_or_b32_sdwa v63, v49, v48 dst_sel:DWORD dst_unused:UNUSED_PAD src0_sel:DWORD src1_sel:WORD_1
	v_or_b32_sdwa v62, v47, v46 dst_sel:DWORD dst_unused:UNUSED_PAD src0_sel:DWORD src1_sel:WORD_1
	v_mfma_f32_16x16x32_bf16 v[46:49], v[10:13], v[42:45], 0
	s_nop 7
	v_and_b32_sdwa v69, v48, v157 dst_sel:DWORD dst_unused:UNUSED_PAD src0_sel:WORD_1 src1_sel:DWORD
	v_and_b32_sdwa v70, v46, v157 dst_sel:DWORD dst_unused:UNUSED_PAD src0_sel:WORD_1 src1_sel:DWORD
	v_add3_u32 v46, v46, v70, s94
	v_add3_u32 v48, v48, v69, s94
	v_and_b32_sdwa v69, v49, v157 dst_sel:DWORD dst_unused:UNUSED_PAD src0_sel:WORD_1 src1_sel:DWORD
	v_and_b32_sdwa v70, v47, v157 dst_sel:DWORD dst_unused:UNUSED_PAD src0_sel:WORD_1 src1_sel:DWORD
	v_add3_u32 v49, v49, v69, s94
	v_add3_u32 v47, v47, v70, s94
	v_and_b32_e32 v49, 0xffff0000, v49
	v_and_b32_e32 v69, 0xffff0000, v47
	v_or_b32_sdwa v47, v49, v48 dst_sel:DWORD dst_unused:UNUSED_PAD src0_sel:DWORD src1_sel:WORD_1
	v_or_b32_sdwa v46, v69, v46 dst_sel:DWORD dst_unused:UNUSED_PAD src0_sel:DWORD src1_sel:WORD_1
	ds_write2_b64 v68, v[62:63], v[46:47] offset0:40 offset1:44
	v_mfma_f32_16x16x32_bf16 v[46:49], v[22:25], v[42:45], 0
	s_nop 7
	v_and_b32_sdwa v62, v48, v157 dst_sel:DWORD dst_unused:UNUSED_PAD src0_sel:WORD_1 src1_sel:DWORD
	v_and_b32_sdwa v63, v46, v157 dst_sel:DWORD dst_unused:UNUSED_PAD src0_sel:WORD_1 src1_sel:DWORD
	v_add3_u32 v46, v46, v63, s94
	v_add3_u32 v48, v48, v62, s94
	v_and_b32_sdwa v62, v49, v157 dst_sel:DWORD dst_unused:UNUSED_PAD src0_sel:WORD_1 src1_sel:DWORD
	v_and_b32_sdwa v63, v47, v157 dst_sel:DWORD dst_unused:UNUSED_PAD src0_sel:WORD_1 src1_sel:DWORD
	v_add3_u32 v49, v49, v62, s94
	v_add3_u32 v47, v47, v63, s94
; DI uint32_t pack2(float a, float b) { return (uint32_t)f2bf(a) | ((uint32_t)f2bf(b) << 16); }
; DI f32x4 mfma16(bf16x8 a, bf16x8 b, f32x4 c) { return __builtin_amdgcn_mfma_f32_16x16x32_bf16(a, b, c, 0, 0, 0); }
; DI void ssm_unit(const Params& p, int l, int g, int row0, int T, float& hr, float& hi, bool write_y, u16* tile) {
;     ...
; #pragma unroll
;   for (int nt = 0; nt < 4; ++nt) {
;     if (nt >= ntile) break;
;     const bf16x8 bu = bu4[nt];
; #pragma unroll
;     for (int mt = 0; mt < 8; ++mt) {
;       const f32x4 a = mfma16(am[mt], bu, f32x4{0.f, 0.f, 0.f, 0.f});
;       uint2 o; o.x = pack2(a[0], a[1]); o.y = pack2(a[2], a[3]);
;       *reinterpret_cast<uint2*>(tile + (nt * 16 + fr) * 136 + mt * 16 + fq * 4) = o;
;     }
;   }
	v_and_b32_e32 v49, 0xffff0000, v49
	v_and_b32_e32 v47, 0xffff0000, v47
	v_or_b32_sdwa v63, v49, v48 dst_sel:DWORD dst_unused:UNUSED_PAD src0_sel:DWORD src1_sel:WORD_1
	v_or_b32_sdwa v62, v47, v46 dst_sel:DWORD dst_unused:UNUSED_PAD src0_sel:DWORD src1_sel:WORD_1
	v_mfma_f32_16x16x32_bf16 v[46:49], v[18:21], v[42:45], 0
	s_nop 7
	v_and_b32_sdwa v69, v48, v157 dst_sel:DWORD dst_unused:UNUSED_PAD src0_sel:WORD_1 src1_sel:DWORD
	v_and_b32_sdwa v70, v46, v157 dst_sel:DWORD dst_unused:UNUSED_PAD src0_sel:WORD_1 src1_sel:DWORD
	v_add3_u32 v46, v46, v70, s94
	v_add3_u32 v48, v48, v69, s94
	v_and_b32_sdwa v69, v49, v157 dst_sel:DWORD dst_unused:UNUSED_PAD src0_sel:WORD_1 src1_sel:DWORD
	v_and_b32_sdwa v70, v47, v157 dst_sel:DWORD dst_unused:UNUSED_PAD src0_sel:WORD_1 src1_sel:DWORD
	v_add3_u32 v49, v49, v69, s94
	v_add3_u32 v47, v47, v70, s94
	v_and_b32_e32 v49, 0xffff0000, v49
	v_and_b32_e32 v69, 0xffff0000, v47
	v_or_b32_sdwa v47, v49, v48 dst_sel:DWORD dst_unused:UNUSED_PAD src0_sel:DWORD src1_sel:WORD_1
	v_or_b32_sdwa v46, v69, v46 dst_sel:DWORD dst_unused:UNUSED_PAD src0_sel:DWORD src1_sel:WORD_1
	ds_write2_b64 v68, v[62:63], v[46:47] offset0:48 offset1:52
	v_mfma_f32_16x16x32_bf16 v[46:49], v[30:33], v[42:45], 0
	v_mfma_f32_16x16x32_bf16 v[42:45], v[26:29], v[42:45], 0
	s_nop 6
	v_and_b32_sdwa v62, v48, v157 dst_sel:DWORD dst_unused:UNUSED_PAD src0_sel:WORD_1 src1_sel:DWORD
	v_and_b32_sdwa v63, v46, v157 dst_sel:DWORD dst_unused:UNUSED_PAD src0_sel:WORD_1 src1_sel:DWORD
	v_add3_u32 v48, v48, v62, s94
	v_and_b32_sdwa v62, v49, v157 dst_sel:DWORD dst_unused:UNUSED_PAD src0_sel:WORD_1 src1_sel:DWORD
	v_add3_u32 v46, v46, v63, s94
	v_and_b32_sdwa v63, v47, v157 dst_sel:DWORD dst_unused:UNUSED_PAD src0_sel:WORD_1 src1_sel:DWORD
	v_add3_u32 v49, v49, v62, s94
	v_add3_u32 v47, v47, v63, s94
	v_and_b32_e32 v49, 0xffff0000, v49
	v_and_b32_e32 v62, 0xffff0000, v47
	v_or_b32_sdwa v47, v49, v48 dst_sel:DWORD dst_unused:UNUSED_PAD src0_sel:DWORD src1_sel:WORD_1
	v_and_b32_sdwa v48, v44, v157 dst_sel:DWORD dst_unused:UNUSED_PAD src0_sel:WORD_1 src1_sel:DWORD
	v_and_b32_sdwa v49, v42, v157 dst_sel:DWORD dst_unused:UNUSED_PAD src0_sel:WORD_1 src1_sel:DWORD
	v_add3_u32 v42, v42, v49, s94
	v_add3_u32 v44, v44, v48, s94
	v_and_b32_sdwa v48, v45, v157 dst_sel:DWORD dst_unused:UNUSED_PAD src0_sel:WORD_1 src1_sel:DWORD
	v_and_b32_sdwa v49, v43, v157 dst_sel:DWORD dst_unused:UNUSED_PAD src0_sel:WORD_1 src1_sel:DWORD
	v_add3_u32 v45, v45, v48, s94
	v_add3_u32 v43, v43, v49, s94
	v_and_b32_e32 v45, 0xffff0000, v45
	v_and_b32_e32 v48, 0xffff0000, v43
	v_or_b32_sdwa v46, v62, v46 dst_sel:DWORD dst_unused:UNUSED_PAD src0_sel:DWORD src1_sel:WORD_1
	v_or_b32_sdwa v43, v45, v44 dst_sel:DWORD dst_unused:UNUSED_PAD src0_sel:DWORD src1_sel:WORD_1
	v_or_b32_sdwa v42, v48, v42 dst_sel:DWORD dst_unused:UNUSED_PAD src0_sel:DWORD src1_sel:WORD_1
	ds_write2_b64 v68, v[46:47], v[42:43] offset0:56 offset1:60
	v_mfma_f32_16x16x32_bf16 v[42:45], v[6:9], v[38:41], 0
	v_mfma_f32_16x16x32_bf16 v[6:9], v[6:9], v[34:37], 0
	s_nop 6
	v_and_b32_sdwa v46, v44, v157 dst_sel:DWORD dst_unused:UNUSED_PAD src0_sel:WORD_1 src1_sel:DWORD
	v_and_b32_sdwa v47, v42, v157 dst_sel:DWORD dst_unused:UNUSED_PAD src0_sel:WORD_1 src1_sel:DWORD
	v_add3_u32 v42, v42, v47, s94
	v_add3_u32 v44, v44, v46, s94
	v_and_b32_sdwa v46, v45, v157 dst_sel:DWORD dst_unused:UNUSED_PAD src0_sel:WORD_1 src1_sel:DWORD
	v_and_b32_sdwa v47, v43, v157 dst_sel:DWORD dst_unused:UNUSED_PAD src0_sel:WORD_1 src1_sel:DWORD
	v_add3_u32 v45, v45, v46, s94
	v_add3_u32 v43, v43, v47, s94
	v_and_b32_e32 v45, 0xffff0000, v45
	v_and_b32_e32 v43, 0xffff0000, v43
	v_or_b32_sdwa v47, v45, v44 dst_sel:DWORD dst_unused:UNUSED_PAD src0_sel:DWORD src1_sel:WORD_1
	v_or_b32_sdwa v46, v43, v42 dst_sel:DWORD dst_unused:UNUSED_PAD src0_sel:DWORD src1_sel:WORD_1
	v_mfma_f32_16x16x32_bf16 v[42:45], v[2:5], v[38:41], 0
	v_mfma_f32_16x16x32_bf16 v[2:5], v[2:5], v[34:37], 0
	s_nop 6
	v_and_b32_sdwa v48, v44, v157 dst_sel:DWORD dst_unused:UNUSED_PAD src0_sel:WORD_1 src1_sel:DWORD
	v_and_b32_sdwa v49, v42, v157 dst_sel:DWORD dst_unused:UNUSED_PAD src0_sel:WORD_1 src1_sel:DWORD
	v_add3_u32 v42, v42, v49, s94
	v_add3_u32 v44, v44, v48, s94
	v_and_b32_sdwa v48, v45, v157 dst_sel:DWORD dst_unused:UNUSED_PAD src0_sel:WORD_1 src1_sel:DWORD
	v_and_b32_sdwa v49, v43, v157 dst_sel:DWORD dst_unused:UNUSED_PAD src0_sel:WORD_1 src1_sel:DWORD
	v_add3_u32 v45, v45, v48, s94
	v_add3_u32 v43, v43, v49, s94
	v_and_b32_e32 v45, 0xffff0000, v45
	v_and_b32_e32 v48, 0xffff0000, v43
	v_or_b32_sdwa v43, v45, v44 dst_sel:DWORD dst_unused:UNUSED_PAD src0_sel:DWORD src1_sel:WORD_1
	v_or_b32_sdwa v42, v48, v42 dst_sel:DWORD dst_unused:UNUSED_PAD src0_sel:DWORD src1_sel:WORD_1
	v_add_u32_e32 v48, 0x2000, v61
	ds_write2_b64 v48, v[46:47], v[42:43] offset0:64 offset1:68
	v_mfma_f32_16x16x32_bf16 v[42:45], v[14:17], v[38:41], 0
	s_nop 7
	v_and_b32_sdwa v46, v44, v157 dst_sel:DWORD dst_unused:UNUSED_PAD src0_sel:WORD_1 src1_sel:DWORD
	v_and_b32_sdwa v47, v42, v157 dst_sel:DWORD dst_unused:UNUSED_PAD src0_sel:WORD_1 src1_sel:DWORD
	v_add3_u32 v42, v42, v47, s94
	v_add3_u32 v44, v44, v46, s94
	v_and_b32_sdwa v46, v45, v157 dst_sel:DWORD dst_unused:UNUSED_PAD src0_sel:WORD_1 src1_sel:DWORD
	v_and_b32_sdwa v47, v43, v157 dst_sel:DWORD dst_unused:UNUSED_PAD src0_sel:WORD_1 src1_sel:DWORD
	v_add3_u32 v45, v45, v46, s94
	v_add3_u32 v43, v43, v47, s94
	v_and_b32_e32 v45, 0xffff0000, v45
	v_and_b32_e32 v43, 0xffff0000, v43
	v_or_b32_sdwa v47, v45, v44 dst_sel:DWORD dst_unused:UNUSED_PAD src0_sel:DWORD src1_sel:WORD_1
	v_or_b32_sdwa v46, v43, v42 dst_sel:DWORD dst_unused:UNUSED_PAD src0_sel:DWORD src1_sel:WORD_1
; DI uint32_t pack2(float a, float b) { return (uint32_t)f2bf(a) | ((uint32_t)f2bf(b) << 16); }
; DI f32x4 mfma16(bf16x8 a, bf16x8 b, f32x4 c) { return __builtin_amdgcn_mfma_f32_16x16x32_bf16(a, b, c, 0, 0, 0); }
; DI void ssm_unit(const Params& p, int l, int g, int row0, int T, float& hr, float& hi, bool write_y, u16* tile) {
;     ...
; #pragma unroll
;   for (int nt = 0; nt < 4; ++nt) {
;     if (nt >= ntile) break;
;     const bf16x8 bu = bu4[nt];
; #pragma unroll
;     for (int mt = 0; mt < 8; ++mt) {
;       const f32x4 a = mfma16(am[mt], bu, f32x4{0.f, 0.f, 0.f, 0.f});
;       uint2 o; o.x = pack2(a[0], a[1]); o.y = pack2(a[2], a[3]);
;       *reinterpret_cast<uint2*>(tile + (nt * 16 + fr) * 136 + mt * 16 + fq * 4) = o;
;     }
;   }
	v_mfma_f32_16x16x32_bf16 v[42:45], v[10:13], v[38:41], 0
	s_nop 7
	v_and_b32_sdwa v49, v44, v157 dst_sel:DWORD dst_unused:UNUSED_PAD src0_sel:WORD_1 src1_sel:DWORD
	v_and_b32_sdwa v62, v42, v157 dst_sel:DWORD dst_unused:UNUSED_PAD src0_sel:WORD_1 src1_sel:DWORD
	v_add3_u32 v42, v42, v62, s94
	v_add3_u32 v44, v44, v49, s94
	v_and_b32_sdwa v49, v45, v157 dst_sel:DWORD dst_unused:UNUSED_PAD src0_sel:WORD_1 src1_sel:DWORD
	v_and_b32_sdwa v62, v43, v157 dst_sel:DWORD dst_unused:UNUSED_PAD src0_sel:WORD_1 src1_sel:DWORD
	v_add3_u32 v45, v45, v49, s94
	v_add3_u32 v43, v43, v62, s94
	v_and_b32_e32 v45, 0xffff0000, v45
	v_and_b32_e32 v49, 0xffff0000, v43
	v_or_b32_sdwa v43, v45, v44 dst_sel:DWORD dst_unused:UNUSED_PAD src0_sel:DWORD src1_sel:WORD_1
	v_or_b32_sdwa v42, v49, v42 dst_sel:DWORD dst_unused:UNUSED_PAD src0_sel:DWORD src1_sel:WORD_1
	ds_write2_b64 v48, v[46:47], v[42:43] offset0:72 offset1:76
	v_mfma_f32_16x16x32_bf16 v[42:45], v[22:25], v[38:41], 0
	s_nop 7
	v_and_b32_sdwa v46, v44, v157 dst_sel:DWORD dst_unused:UNUSED_PAD src0_sel:WORD_1 src1_sel:DWORD
	v_and_b32_sdwa v47, v42, v157 dst_sel:DWORD dst_unused:UNUSED_PAD src0_sel:WORD_1 src1_sel:DWORD
	v_add3_u32 v42, v42, v47, s94
	v_add3_u32 v44, v44, v46, s94
	v_and_b32_sdwa v46, v45, v157 dst_sel:DWORD dst_unused:UNUSED_PAD src0_sel:WORD_1 src1_sel:DWORD
	v_and_b32_sdwa v47, v43, v157 dst_sel:DWORD dst_unused:UNUSED_PAD src0_sel:WORD_1 src1_sel:DWORD
	v_add3_u32 v45, v45, v46, s94
	v_add3_u32 v43, v43, v47, s94
	v_and_b32_e32 v45, 0xffff0000, v45
	v_and_b32_e32 v43, 0xffff0000, v43
	v_or_b32_sdwa v47, v45, v44 dst_sel:DWORD dst_unused:UNUSED_PAD src0_sel:DWORD src1_sel:WORD_1
	v_or_b32_sdwa v46, v43, v42 dst_sel:DWORD dst_unused:UNUSED_PAD src0_sel:DWORD src1_sel:WORD_1
	v_mfma_f32_16x16x32_bf16 v[42:45], v[18:21], v[38:41], 0
	s_nop 7
	v_and_b32_sdwa v49, v44, v157 dst_sel:DWORD dst_unused:UNUSED_PAD src0_sel:WORD_1 src1_sel:DWORD
	v_and_b32_sdwa v62, v42, v157 dst_sel:DWORD dst_unused:UNUSED_PAD src0_sel:WORD_1 src1_sel:DWORD
	v_add3_u32 v42, v42, v62, s94
	v_add3_u32 v44, v44, v49, s94
	v_and_b32_sdwa v49, v45, v157 dst_sel:DWORD dst_unused:UNUSED_PAD src0_sel:WORD_1 src1_sel:DWORD
	v_and_b32_sdwa v62, v43, v157 dst_sel:DWORD dst_unused:UNUSED_PAD src0_sel:WORD_1 src1_sel:DWORD
	v_add3_u32 v45, v45, v49, s94
	v_add3_u32 v43, v43, v62, s94
	v_and_b32_e32 v45, 0xffff0000, v45
	v_and_b32_e32 v49, 0xffff0000, v43
	v_or_b32_sdwa v43, v45, v44 dst_sel:DWORD dst_unused:UNUSED_PAD src0_sel:DWORD src1_sel:WORD_1
	v_or_b32_sdwa v42, v49, v42 dst_sel:DWORD dst_unused:UNUSED_PAD src0_sel:DWORD src1_sel:WORD_1
	ds_write2_b64 v48, v[46:47], v[42:43] offset0:80 offset1:84
	v_mfma_f32_16x16x32_bf16 v[42:45], v[30:33], v[38:41], 0
	v_mfma_f32_16x16x32_bf16 v[38:41], v[26:29], v[38:41], 0
	s_nop 6
	v_and_b32_sdwa v46, v44, v157 dst_sel:DWORD dst_unused:UNUSED_PAD src0_sel:WORD_1 src1_sel:DWORD
	v_and_b32_sdwa v47, v42, v157 dst_sel:DWORD dst_unused:UNUSED_PAD src0_sel:WORD_1 src1_sel:DWORD
	v_add3_u32 v44, v44, v46, s94
	v_and_b32_sdwa v46, v45, v157 dst_sel:DWORD dst_unused:UNUSED_PAD src0_sel:WORD_1 src1_sel:DWORD
	v_add3_u32 v42, v42, v47, s94
	v_and_b32_sdwa v47, v43, v157 dst_sel:DWORD dst_unused:UNUSED_PAD src0_sel:WORD_1 src1_sel:DWORD
	v_add3_u32 v45, v45, v46, s94
	v_add3_u32 v43, v43, v47, s94
	v_and_b32_e32 v45, 0xffff0000, v45
	v_and_b32_e32 v46, 0xffff0000, v43
	v_or_b32_sdwa v43, v45, v44 dst_sel:DWORD dst_unused:UNUSED_PAD src0_sel:DWORD src1_sel:WORD_1
	v_and_b32_sdwa v44, v40, v157 dst_sel:DWORD dst_unused:UNUSED_PAD src0_sel:WORD_1 src1_sel:DWORD
	v_and_b32_sdwa v45, v38, v157 dst_sel:DWORD dst_unused:UNUSED_PAD src0_sel:WORD_1 src1_sel:DWORD
	v_add3_u32 v38, v38, v45, s94
	v_add3_u32 v40, v40, v44, s94
	v_and_b32_sdwa v44, v41, v157 dst_sel:DWORD dst_unused:UNUSED_PAD src0_sel:WORD_1 src1_sel:DWORD
	v_and_b32_sdwa v45, v39, v157 dst_sel:DWORD dst_unused:UNUSED_PAD src0_sel:WORD_1 src1_sel:DWORD
	v_add3_u32 v41, v41, v44, s94
	v_add3_u32 v39, v39, v45, s94
	v_and_b32_e32 v41, 0xffff0000, v41
	v_and_b32_e32 v44, 0xffff0000, v39
	v_or_b32_sdwa v42, v46, v42 dst_sel:DWORD dst_unused:UNUSED_PAD src0_sel:DWORD src1_sel:WORD_1
	v_or_b32_sdwa v39, v41, v40 dst_sel:DWORD dst_unused:UNUSED_PAD src0_sel:DWORD src1_sel:WORD_1
	v_or_b32_sdwa v38, v44, v38 dst_sel:DWORD dst_unused:UNUSED_PAD src0_sel:DWORD src1_sel:WORD_1
	ds_write2_b64 v48, v[42:43], v[38:39] offset0:88 offset1:92
	v_and_b32_sdwa v38, v8, v157 dst_sel:DWORD dst_unused:UNUSED_PAD src0_sel:WORD_1 src1_sel:DWORD
	v_and_b32_sdwa v39, v6, v157 dst_sel:DWORD dst_unused:UNUSED_PAD src0_sel:WORD_1 src1_sel:DWORD
	v_add3_u32 v8, v8, v38, s94
	v_and_b32_sdwa v38, v9, v157 dst_sel:DWORD dst_unused:UNUSED_PAD src0_sel:WORD_1 src1_sel:DWORD
	v_add3_u32 v6, v6, v39, s94
	v_and_b32_sdwa v39, v7, v157 dst_sel:DWORD dst_unused:UNUSED_PAD src0_sel:WORD_1 src1_sel:DWORD
	v_add3_u32 v9, v9, v38, s94
	v_add3_u32 v7, v7, v39, s94
	v_and_b32_e32 v9, 0xffff0000, v9
	v_and_b32_e32 v38, 0xffff0000, v7
	v_or_b32_sdwa v7, v9, v8 dst_sel:DWORD dst_unused:UNUSED_PAD src0_sel:DWORD src1_sel:WORD_1
	v_and_b32_sdwa v8, v4, v157 dst_sel:DWORD dst_unused:UNUSED_PAD src0_sel:WORD_1 src1_sel:DWORD
	v_and_b32_sdwa v9, v2, v157 dst_sel:DWORD dst_unused:UNUSED_PAD src0_sel:WORD_1 src1_sel:DWORD
	v_add3_u32 v2, v2, v9, s94
	v_add3_u32 v4, v4, v8, s94
	v_and_b32_sdwa v8, v5, v157 dst_sel:DWORD dst_unused:UNUSED_PAD src0_sel:WORD_1 src1_sel:DWORD
	v_and_b32_sdwa v9, v3, v157 dst_sel:DWORD dst_unused:UNUSED_PAD src0_sel:WORD_1 src1_sel:DWORD
	v_add3_u32 v5, v5, v8, s94
	v_add3_u32 v3, v3, v9, s94
	v_and_b32_e32 v5, 0xffff0000, v5
	v_and_b32_e32 v8, 0xffff0000, v3
; DI float bf2f(u16 h) { return __uint_as_float(((uint32_t)h) << 16); }
; DI uint32_t pack2(float a, float b) { return (uint32_t)f2bf(a) | ((uint32_t)f2bf(b) << 16); }
; DI void wave_lds_sync() { asm volatile("s_waitcnt lgkmcnt(0)" ::: "memory"); }
; DI f32x4 mfma16(bf16x8 a, bf16x8 b, f32x4 c) { return __builtin_amdgcn_mfma_f32_16x16x32_bf16(a, b, c, 0, 0, 0); }
; DI void ssm_unit(const Params& p, int l, int g, int row0, int T, float& hr, float& hi, bool write_y, u16* tile) {
;     ...
; #pragma unroll
;   for (int nt = 0; nt < 4; ++nt) {
;     if (nt >= ntile) break;
;     const bf16x8 bu = bu4[nt];
; #pragma unroll
;     for (int mt = 0; mt < 8; ++mt) {
;       const f32x4 a = mfma16(am[mt], bu, f32x4{0.f, 0.f, 0.f, 0.f});
;       uint2 o; o.x = pack2(a[0], a[1]); o.y = pack2(a[2], a[3]);
;       *reinterpret_cast<uint2*>(tile + (nt * 16 + fr) * 136 + mt * 16 + fq * 4) = o;
;     }
;   }
;   wave_lds_sync();
;   for (int t = 0; t < T; ++t) {
;     const float br = bf2f(tile[t * 136 + lane]), bi = bf2f(tile[t * 136 + 64 + lane]);
	v_or_b32_sdwa v6, v38, v6 dst_sel:DWORD dst_unused:UNUSED_PAD src0_sel:DWORD src1_sel:WORD_1
	v_or_b32_sdwa v3, v5, v4 dst_sel:DWORD dst_unused:UNUSED_PAD src0_sel:DWORD src1_sel:WORD_1
	v_or_b32_sdwa v2, v8, v2 dst_sel:DWORD dst_unused:UNUSED_PAD src0_sel:DWORD src1_sel:WORD_1
	v_add_u32_e32 v8, 0x3000, v61
	ds_write2_b64 v8, v[6:7], v[2:3] offset0:96 offset1:100
	v_mfma_f32_16x16x32_bf16 v[2:5], v[14:17], v[34:37], 0
	s_nop 7
	v_and_b32_sdwa v6, v4, v157 dst_sel:DWORD dst_unused:UNUSED_PAD src0_sel:WORD_1 src1_sel:DWORD
	v_and_b32_sdwa v7, v2, v157 dst_sel:DWORD dst_unused:UNUSED_PAD src0_sel:WORD_1 src1_sel:DWORD
	v_add3_u32 v2, v2, v7, s94
	v_add3_u32 v4, v4, v6, s94
	v_and_b32_sdwa v6, v5, v157 dst_sel:DWORD dst_unused:UNUSED_PAD src0_sel:WORD_1 src1_sel:DWORD
	v_and_b32_sdwa v7, v3, v157 dst_sel:DWORD dst_unused:UNUSED_PAD src0_sel:WORD_1 src1_sel:DWORD
	v_add3_u32 v5, v5, v6, s94
	v_add3_u32 v3, v3, v7, s94
	v_and_b32_e32 v5, 0xffff0000, v5
	v_and_b32_e32 v3, 0xffff0000, v3
	v_or_b32_sdwa v7, v5, v4 dst_sel:DWORD dst_unused:UNUSED_PAD src0_sel:DWORD src1_sel:WORD_1
	v_or_b32_sdwa v6, v3, v2 dst_sel:DWORD dst_unused:UNUSED_PAD src0_sel:DWORD src1_sel:WORD_1
	v_mfma_f32_16x16x32_bf16 v[2:5], v[10:13], v[34:37], 0
	s_nop 7
	v_and_b32_sdwa v9, v4, v157 dst_sel:DWORD dst_unused:UNUSED_PAD src0_sel:WORD_1 src1_sel:DWORD
	v_and_b32_sdwa v10, v2, v157 dst_sel:DWORD dst_unused:UNUSED_PAD src0_sel:WORD_1 src1_sel:DWORD
	v_add3_u32 v2, v2, v10, s94
	v_add3_u32 v4, v4, v9, s94
	v_and_b32_sdwa v9, v5, v157 dst_sel:DWORD dst_unused:UNUSED_PAD src0_sel:WORD_1 src1_sel:DWORD
	v_and_b32_sdwa v10, v3, v157 dst_sel:DWORD dst_unused:UNUSED_PAD src0_sel:WORD_1 src1_sel:DWORD
	v_add3_u32 v5, v5, v9, s94
	v_add3_u32 v3, v3, v10, s94
	v_and_b32_e32 v5, 0xffff0000, v5
	v_and_b32_e32 v9, 0xffff0000, v3
	v_or_b32_sdwa v3, v5, v4 dst_sel:DWORD dst_unused:UNUSED_PAD src0_sel:DWORD src1_sel:WORD_1
	v_or_b32_sdwa v2, v9, v2 dst_sel:DWORD dst_unused:UNUSED_PAD src0_sel:DWORD src1_sel:WORD_1
	ds_write2_b64 v8, v[6:7], v[2:3] offset0:104 offset1:108
	v_mfma_f32_16x16x32_bf16 v[2:5], v[22:25], v[34:37], 0
	s_nop 7
	v_and_b32_sdwa v6, v4, v157 dst_sel:DWORD dst_unused:UNUSED_PAD src0_sel:WORD_1 src1_sel:DWORD
	v_and_b32_sdwa v7, v2, v157 dst_sel:DWORD dst_unused:UNUSED_PAD src0_sel:WORD_1 src1_sel:DWORD
	v_add3_u32 v2, v2, v7, s94
	v_add3_u32 v4, v4, v6, s94
	v_and_b32_sdwa v6, v5, v157 dst_sel:DWORD dst_unused:UNUSED_PAD src0_sel:WORD_1 src1_sel:DWORD
	v_and_b32_sdwa v7, v3, v157 dst_sel:DWORD dst_unused:UNUSED_PAD src0_sel:WORD_1 src1_sel:DWORD
	v_add3_u32 v5, v5, v6, s94
	v_add3_u32 v3, v3, v7, s94
	v_and_b32_e32 v5, 0xffff0000, v5
	v_and_b32_e32 v3, 0xffff0000, v3
	v_or_b32_sdwa v7, v5, v4 dst_sel:DWORD dst_unused:UNUSED_PAD src0_sel:DWORD src1_sel:WORD_1
	v_or_b32_sdwa v6, v3, v2 dst_sel:DWORD dst_unused:UNUSED_PAD src0_sel:DWORD src1_sel:WORD_1
	v_mfma_f32_16x16x32_bf16 v[2:5], v[18:21], v[34:37], 0
	s_nop 7
	v_and_b32_sdwa v9, v4, v157 dst_sel:DWORD dst_unused:UNUSED_PAD src0_sel:WORD_1 src1_sel:DWORD
	v_and_b32_sdwa v10, v2, v157 dst_sel:DWORD dst_unused:UNUSED_PAD src0_sel:WORD_1 src1_sel:DWORD
	v_add3_u32 v2, v2, v10, s94
	v_add3_u32 v4, v4, v9, s94
	v_and_b32_sdwa v9, v5, v157 dst_sel:DWORD dst_unused:UNUSED_PAD src0_sel:WORD_1 src1_sel:DWORD
	v_and_b32_sdwa v10, v3, v157 dst_sel:DWORD dst_unused:UNUSED_PAD src0_sel:WORD_1 src1_sel:DWORD
	v_add3_u32 v5, v5, v9, s94
	v_add3_u32 v3, v3, v10, s94
	v_and_b32_e32 v5, 0xffff0000, v5
	v_and_b32_e32 v9, 0xffff0000, v3
	v_or_b32_sdwa v3, v5, v4 dst_sel:DWORD dst_unused:UNUSED_PAD src0_sel:DWORD src1_sel:WORD_1
	v_or_b32_sdwa v2, v9, v2 dst_sel:DWORD dst_unused:UNUSED_PAD src0_sel:DWORD src1_sel:WORD_1
	ds_write2_b64 v8, v[6:7], v[2:3] offset0:112 offset1:116
	v_mfma_f32_16x16x32_bf16 v[2:5], v[30:33], v[34:37], 0
	s_nop 7
	v_and_b32_sdwa v6, v4, v157 dst_sel:DWORD dst_unused:UNUSED_PAD src0_sel:WORD_1 src1_sel:DWORD
	v_and_b32_sdwa v7, v2, v157 dst_sel:DWORD dst_unused:UNUSED_PAD src0_sel:WORD_1 src1_sel:DWORD
	v_add3_u32 v2, v2, v7, s94
	v_add3_u32 v4, v4, v6, s94
	v_and_b32_sdwa v6, v5, v157 dst_sel:DWORD dst_unused:UNUSED_PAD src0_sel:WORD_1 src1_sel:DWORD
	v_and_b32_sdwa v7, v3, v157 dst_sel:DWORD dst_unused:UNUSED_PAD src0_sel:WORD_1 src1_sel:DWORD
	v_add3_u32 v5, v5, v6, s94
	v_add3_u32 v3, v3, v7, s94
	v_and_b32_e32 v5, 0xffff0000, v5
	v_and_b32_e32 v3, 0xffff0000, v3
	v_or_b32_sdwa v7, v5, v4 dst_sel:DWORD dst_unused:UNUSED_PAD src0_sel:DWORD src1_sel:WORD_1
	v_or_b32_sdwa v6, v3, v2 dst_sel:DWORD dst_unused:UNUSED_PAD src0_sel:DWORD src1_sel:WORD_1
	v_mfma_f32_16x16x32_bf16 v[2:5], v[26:29], v[34:37], 0
	s_nop 7
	v_and_b32_sdwa v9, v4, v157 dst_sel:DWORD dst_unused:UNUSED_PAD src0_sel:WORD_1 src1_sel:DWORD
	v_and_b32_sdwa v10, v2, v157 dst_sel:DWORD dst_unused:UNUSED_PAD src0_sel:WORD_1 src1_sel:DWORD
	v_add3_u32 v2, v2, v10, s94
	v_add3_u32 v4, v4, v9, s94
	v_and_b32_sdwa v9, v5, v157 dst_sel:DWORD dst_unused:UNUSED_PAD src0_sel:WORD_1 src1_sel:DWORD
	v_and_b32_sdwa v10, v3, v157 dst_sel:DWORD dst_unused:UNUSED_PAD src0_sel:WORD_1 src1_sel:DWORD
	v_add3_u32 v5, v5, v9, s94
	v_add3_u32 v3, v3, v10, s94
	v_and_b32_e32 v5, 0xffff0000, v5
	v_and_b32_e32 v9, 0xffff0000, v3
	v_or_b32_sdwa v3, v5, v4 dst_sel:DWORD dst_unused:UNUSED_PAD src0_sel:DWORD src1_sel:WORD_1
	v_or_b32_sdwa v2, v9, v2 dst_sel:DWORD dst_unused:UNUSED_PAD src0_sel:DWORD src1_sel:WORD_1
	ds_write2_b64 v8, v[6:7], v[2:3] offset0:120 offset1:124
	s_waitcnt lgkmcnt(0)
	v_xor_b32_e32 v5, 0x80000000, v55
	v_lshl_add_u32 v4, v65, 1, v64
	v_mov_b32_e32 v2, v54
	v_mov_b32_e32 v3, v54
	v_mov_b32_e32 v54, v5
	v_add_u32_e32 v5, s50, v4
	ds_read_u16 v198, v5
	ds_read_u16 v199, v5 offset:128
	ds_read_u16 v200, v5 offset:272
	ds_read_u16 v201, v5 offset:400
	ds_read_u16 v202, v5 offset:544
	ds_read_u16 v203, v5 offset:672
	ds_read_u16 v204, v5 offset:816
	ds_read_u16 v205, v5 offset:944
; DI u16 f2bf(float x) { uint32_t u = __float_as_uint(x); u += 0x7fffu + ((u >> 16) & 1u); return (u16)(u >> 16); }
; DI float bf2f(u16 h) { return __uint_as_float(((uint32_t)h) << 16); }
; DI void wave_lds_sync() { asm volatile("s_waitcnt lgkmcnt(0)" ::: "memory"); }
; DI void ssm_unit(const Params& p, int l, int g, int row0, int T, float& hr, float& hi, bool write_y, u16* tile) {
;     ...
;   for (int t = 0; t < T; ++t) {
;     const float br = bf2f(tile[t * 136 + lane]), bi = bf2f(tile[t * 136 + 64 + lane]);
;     const float nhr = fmaf(abr, hr, fmaf(-abi, hi, br));
;     const float nhi = fmaf(abr, hi, fmaf(abi, hr, bi));
;     hr = nhr; hi = nhi;
;     if (write_y) { tile[t * 136 + lane] = f2bf(hr); tile[t * 136 + 64 + lane] = f2bf(hi); }
;   }
;   if (!write_y) return;
;   wave_lds_sync();
;   bf16x8 cm[4];
; #pragma unroll
;   for (int ks = 0; ks < 4; ++ks) cm[ks] = ldg8(((u16*)(p.ws + WS_Cmat)) + ((size_t)lg * 16 + fr) * 128 + ks * 32 + fq * 8);
;   const float dsk = p.d_skip[(size_t)lg * 16 + fr];
;   u16 uv[4][4];
; #pragma unroll
;   for (int mt = 0; mt < 4; ++mt)
; #pragma unroll
;     for (int j = 0; j < 4; ++j) uv[mt][j] = mt < ntile ? ((u16*)(p.ws + WS_U))[(size_t)(row0 + mt * 16 + fq * 4 + j) * 512 + g * 16 + fr] : (u16)0;
.LBB0_254:
	v_add_u32_e32 v5, s50, v4
	s_waitcnt lgkmcnt(0)
	v_lshlrev_b32_e32 v206, 16, v198
	v_lshlrev_b32_e32 v207, 16, v199
	v_lshlrev_b32_e32 v208, 16, v200
	v_lshlrev_b32_e32 v209, 16, v201
	v_lshlrev_b32_e32 v210, 16, v202
	v_lshlrev_b32_e32 v211, 16, v203
	v_lshlrev_b32_e32 v212, 16, v204
	v_lshlrev_b32_e32 v213, 16, v205
	ds_read_u16 v198, v5 offset:1088
	ds_read_u16 v199, v5 offset:1216
	ds_read_u16 v200, v5 offset:1360
	ds_read_u16 v201, v5 offset:1488
	ds_read_u16 v202, v5 offset:1632
	ds_read_u16 v203, v5 offset:1760
	ds_read_u16 v204, v5 offset:1904
	ds_read_u16 v205, v5 offset:2032
	s_addk_i32 s50, 0x440
	s_cmpk_lg_i32 s50, 0x4400
	v_pk_fma_f32 v[206:207], v[54:55], v[56:57], v[206:207] op_sel:[0,1,0] op_sel_hi:[1,0,1]
	s_nop 0
	v_pk_fma_f32 v[6:7], v[2:3], v[56:57], v[206:207]
	s_nop 0
	v_bfe_u32 v8, v6, 16, 1
	v_add3_u32 v8, v6, v8, s94
	ds_write_b16_d16_hi v5, v8
	v_bfe_u32 v9, v7, 16, 1
	v_add3_u32 v9, v7, v9, s94
	ds_write_b16_d16_hi v5, v9 offset:128
	v_pk_fma_f32 v[208:209], v[54:55], v[6:7], v[208:209] op_sel:[0,1,0] op_sel_hi:[1,0,1]
	s_nop 0
	v_pk_fma_f32 v[6:7], v[2:3], v[6:7], v[208:209]
	s_nop 0
	v_bfe_u32 v8, v6, 16, 1
	v_add3_u32 v8, v6, v8, s94
	ds_write_b16_d16_hi v5, v8 offset:272
	v_bfe_u32 v9, v7, 16, 1
	v_add3_u32 v9, v7, v9, s94
	ds_write_b16_d16_hi v5, v9 offset:400
	v_pk_fma_f32 v[210:211], v[54:55], v[6:7], v[210:211] op_sel:[0,1,0] op_sel_hi:[1,0,1]
	s_nop 0
	v_pk_fma_f32 v[6:7], v[2:3], v[6:7], v[210:211]
	s_nop 0
	v_bfe_u32 v8, v6, 16, 1
	v_add3_u32 v8, v6, v8, s94
	ds_write_b16_d16_hi v5, v8 offset:544
	v_bfe_u32 v9, v7, 16, 1
	v_add3_u32 v9, v7, v9, s94
	ds_write_b16_d16_hi v5, v9 offset:672
	v_pk_fma_f32 v[212:213], v[54:55], v[6:7], v[212:213] op_sel:[0,1,0] op_sel_hi:[1,0,1]
	s_nop 0
	v_pk_fma_f32 v[56:57], v[2:3], v[6:7], v[212:213]
	s_nop 0
	v_bfe_u32 v8, v56, 16, 1
	v_add3_u32 v8, v56, v8, s94
	ds_write_b16_d16_hi v5, v8 offset:816
	v_bfe_u32 v9, v57, 16, 1
	v_add3_u32 v9, v57, v9, s94
	ds_write_b16_d16_hi v5, v9 offset:944
	s_cbranch_scc1 .LBB0_254
	v_lshlrev_b64 v[2:3], 12, v[52:53]
	v_lshl_add_u64 v[2:3], s[6:7], 0, v[2:3]
	v_lshlrev_b32_e32 v4, 8, v66
	v_mov_b32_e32 v5, v1
	v_lshlrev_b64 v[6:7], 6, v[52:53]
	v_lshl_add_u64 v[2:3], v[2:3], 0, v[4:5]
	v_lshl_add_u64 v[6:7], s[56:57], 0, v[6:7]
	v_lshlrev_b32_e32 v8, 2, v66
	v_mov_b32_e32 v9, v1
	s_waitcnt lgkmcnt(0)
	v_lshl_add_u64 v[2:3], v[2:3], 0, v[0:1]
	v_lshl_add_u64 v[6:7], v[6:7], 0, v[8:9]
	global_load_dwordx4 v[26:29], v[2:3], off
	global_load_dwordx4 v[22:25], v[2:3], off offset:64
	global_load_dwordx4 v[18:21], v[2:3], off offset:128
	s_nop 0
	global_load_dwordx4 v[2:5], v[2:3], off offset:192
	v_lshlrev_b32_e32 v8, 1, v66
	global_load_dword v65, v[6:7], off
	v_or_b32_e32 v6, v60, v67
	v_ashrrev_i32_e32 v7, 31, v6
	v_lshl_add_u64 v[8:9], v[58:59], 0, v[8:9]
	v_lshlrev_b64 v[10:11], 10, v[6:7]
	v_lshl_add_u64 v[62:63], v[8:9], 0, v[10:11]
	v_or_b32_e32 v10, 1, v6
	v_ashrrev_i32_e32 v11, 31, v10
	v_lshlrev_b64 v[10:11], 10, v[10:11]
	v_lshl_add_u64 v[60:61], v[8:9], 0, v[10:11]
	v_or_b32_e32 v10, 2, v6
	v_ashrrev_i32_e32 v11, 31, v10
	v_lshlrev_b64 v[10:11], 10, v[10:11]
	v_lshl_add_u64 v[58:59], v[8:9], 0, v[10:11]
	v_or_b32_e32 v10, 3, v6
	v_ashrrev_i32_e32 v11, 31, v10
	v_lshlrev_b64 v[10:11], 10, v[10:11]
	v_lshl_add_u64 v[56:57], v[8:9], 0, v[10:11]
	v_or_b32_e32 v10, 16, v6
	v_ashrrev_i32_e32 v11, 31, v10
	v_lshlrev_b64 v[10:11], 10, v[10:11]
	v_lshl_add_u64 v[54:55], v[8:9], 0, v[10:11]
	v_or_b32_e32 v10, 17, v6
	v_ashrrev_i32_e32 v11, 31, v10
	v_lshlrev_b64 v[10:11], 10, v[10:11]
	v_lshl_add_u64 v[52:53], v[8:9], 0, v[10:11]
	v_or_b32_e32 v10, 18, v6
	v_ashrrev_i32_e32 v11, 31, v10
	v_lshlrev_b64 v[10:11], 10, v[10:11]
	v_lshl_add_u64 v[48:49], v[8:9], 0, v[10:11]
	v_or_b32_e32 v10, 19, v6
	v_ashrrev_i32_e32 v11, 31, v10
	v_lshlrev_b64 v[10:11], 10, v[10:11]
	v_lshl_add_u64 v[46:47], v[8:9], 0, v[10:11]
	v_or_b32_e32 v10, 32, v6
	v_ashrrev_i32_e32 v11, 31, v10
	v_lshlrev_b64 v[10:11], 10, v[10:11]
	v_lshl_add_u64 v[44:45], v[8:9], 0, v[10:11]
	global_load_ushort v7, v[44:45], off
	v_or_b32_e32 v10, 33, v6
	v_ashrrev_i32_e32 v11, 31, v10
	v_lshlrev_b64 v[10:11], 10, v[10:11]
	v_lshl_add_u64 v[42:43], v[8:9], 0, v[10:11]
	v_or_b32_e32 v10, 34, v6
	v_ashrrev_i32_e32 v11, 31, v10
	v_lshlrev_b64 v[10:11], 10, v[10:11]
	v_lshl_add_u64 v[40:41], v[8:9], 0, v[10:11]
	v_or_b32_e32 v10, 35, v6
	v_ashrrev_i32_e32 v11, 31, v10
	v_lshlrev_b64 v[10:11], 10, v[10:11]
	v_lshl_add_u64 v[38:39], v[8:9], 0, v[10:11]
	v_or_b32_e32 v10, 48, v6
	v_ashrrev_i32_e32 v11, 31, v10
	v_lshlrev_b64 v[10:11], 10, v[10:11]
	v_lshl_add_u64 v[36:37], v[8:9], 0, v[10:11]
	v_or_b32_e32 v10, 49, v6
	v_ashrrev_i32_e32 v11, 31, v10
	v_lshlrev_b64 v[10:11], 10, v[10:11]
	v_lshl_add_u64 v[34:35], v[8:9], 0, v[10:11]
	v_or_b32_e32 v10, 50, v6
	v_ashrrev_i32_e32 v11, 31, v10
	v_lshlrev_b64 v[10:11], 10, v[10:11]
	v_lshl_add_u64 v[32:33], v[8:9], 0, v[10:11]
	v_or_b32_e32 v6, 51, v6
	v_add3_u32 v0, v64, v0, v74
	ds_read_b128 v[10:13], v0 offset:64
	ds_read_b128 v[74:77], v0 offset:8768
	s_waitcnt vmcnt(0) lgkmcnt(0)
	v_lshlrev_b32_e32 v73, 16, v7
	global_load_ushort v7, v[42:43], off
	s_waitcnt vmcnt(0) lgkmcnt(0)
	v_lshlrev_b32_e32 v72, 16, v7
	global_load_ushort v7, v[40:41], off
	s_waitcnt vmcnt(0) lgkmcnt(0)
	v_lshlrev_b32_e32 v71, 16, v7
	global_load_ushort v7, v[38:39], off
	s_waitcnt vmcnt(0) lgkmcnt(0)
	v_lshlrev_b32_e32 v70, 16, v7
	global_load_ushort v7, v[36:37], off
	s_waitcnt vmcnt(0) lgkmcnt(0)
	v_lshlrev_b32_e32 v69, 16, v7
	global_load_ushort v7, v[34:35], off
	s_waitcnt vmcnt(0) lgkmcnt(0)
	v_lshlrev_b32_e32 v68, 16, v7
	global_load_ushort v7, v[32:33], off
	s_waitcnt vmcnt(0) lgkmcnt(0)
; DI u16 f2bf(float x) { uint32_t u = __float_as_uint(x); u += 0x7fffu + ((u >> 16) & 1u); return (u16)(u >> 16); }
; DI float bf2f(u16 h) { return __uint_as_float(((uint32_t)h) << 16); }
; DI float geluf_(float v) { return v * sigmoidf_(1.5957691216f * (v + 0.044715f * v * v * v)); }
; DI f32x4 mfma16(bf16x8 a, bf16x8 b, f32x4 c) { return __builtin_amdgcn_mfma_f32_16x16x32_bf16(a, b, c, 0, 0, 0); }
; DI void ssm_unit(const Params& p, int l, int g, int row0, int T, float& hr, float& hi, bool write_y, u16* tile) {
;     ...
;   f32x4 ya[4];
; #pragma unroll
;   for (int mt = 0; mt < 4; ++mt) {
;     f32x4 a = {0.f, 0.f, 0.f, 0.f};
;     if (mt < ntile) {
; #pragma unroll
;       for (int ks = 0; ks < 4; ++ks) a = mfma16(*reinterpret_cast<const bf16x8*>(tile + (mt * 16 + fr) * 136 + ks * 32 + fq * 8), cm[ks], a);
;     }
;     ya[mt] = a;
;   }
; #pragma unroll
;   for (int mt = 0; mt < 4; ++mt) {
;     if (mt < ntile) {
; #pragma unroll
;       for (int j = 0; j < 4; ++j) {
;         u16* up = ((u16*)(p.ws + WS_U)) + (size_t)(row0 + mt * 16 + fq * 4 + j) * 512 + g * 16 + fr;
;         const float y = ya[mt][j] + dsk * bf2f(uv[mt][j]);
;         *up = f2bf(geluf_(y));
;       }
	v_lshlrev_b32_e32 v67, 16, v7
	v_ashrrev_i32_e32 v7, 31, v6
	v_lshlrev_b64 v[6:7], 10, v[6:7]
	v_lshl_add_u64 v[30:31], v[8:9], 0, v[6:7]
	global_load_ushort v6, v[30:31], off
	s_waitcnt vmcnt(0) lgkmcnt(0)
	v_lshlrev_b32_e32 v66, 16, v6
	ds_read_b128 v[6:9], v0
	s_waitcnt lgkmcnt(0)
	v_mfma_f32_16x16x32_bf16 v[6:9], v[6:9], v[26:29], 0
	v_mfma_f32_16x16x32_bf16 v[6:9], v[10:13], v[22:25], v[6:9]
	ds_read_b128 v[10:13], v0 offset:128
	s_waitcnt lgkmcnt(0)
	v_mfma_f32_16x16x32_bf16 v[6:9], v[10:13], v[18:21], v[6:9]
	ds_read_b128 v[10:13], v0 offset:192
	s_waitcnt lgkmcnt(0)
	v_mfma_f32_16x16x32_bf16 v[14:17], v[10:13], v[2:5], v[6:9]
	s_nop 4
	ds_read_b128 v[6:9], v0 offset:4352
	ds_read_b128 v[10:13], v0 offset:4416
	s_waitcnt lgkmcnt(1)
	v_mfma_f32_16x16x32_bf16 v[6:9], v[6:9], v[26:29], 0
	s_waitcnt lgkmcnt(0)
	v_mfma_f32_16x16x32_bf16 v[6:9], v[10:13], v[22:25], v[6:9]
	ds_read_b128 v[10:13], v0 offset:4480
	s_waitcnt lgkmcnt(0)
	v_mfma_f32_16x16x32_bf16 v[6:9], v[10:13], v[18:21], v[6:9]
	ds_read_b128 v[10:13], v0 offset:4544
	s_waitcnt lgkmcnt(0)
	v_mfma_f32_16x16x32_bf16 v[10:13], v[10:13], v[2:5], v[6:9]
	s_nop 4
	ds_read_b128 v[6:9], v0 offset:8704
	s_waitcnt lgkmcnt(0)
	v_mfma_f32_16x16x32_bf16 v[6:9], v[6:9], v[26:29], 0
	v_mfma_f32_16x16x32_bf16 v[6:9], v[74:77], v[22:25], v[6:9]
	ds_read_b128 v[74:77], v0 offset:8832
	s_waitcnt lgkmcnt(0)
	v_mfma_f32_16x16x32_bf16 v[6:9], v[74:77], v[18:21], v[6:9]
	ds_read_b128 v[74:77], v0 offset:8896
	s_waitcnt lgkmcnt(0)
	v_mfma_f32_16x16x32_bf16 v[6:9], v[74:77], v[2:5], v[6:9]
	ds_read_b128 v[74:77], v0 offset:13056
	s_nop 6
	v_fmac_f32_e32 v9, v65, v70
	s_waitcnt lgkmcnt(0)
	v_mfma_f32_16x16x32_bf16 v[26:29], v[74:77], v[26:29], 0
	ds_read_b128 v[74:77], v0 offset:13120
	s_waitcnt lgkmcnt(0)
	v_mfma_f32_16x16x32_bf16 v[22:25], v[74:77], v[22:25], v[26:29]
	s_nop 4
	ds_read_b128 v[26:29], v0 offset:13184
	s_waitcnt lgkmcnt(0)
	v_mfma_f32_16x16x32_bf16 v[18:21], v[26:29], v[18:21], v[22:25]
	s_nop 2
	ds_read_b128 v[22:25], v0 offset:13248
	global_load_ushort v0, v[62:63], off
	s_waitcnt vmcnt(0) lgkmcnt(0)
	v_lshlrev_b32_e32 v0, 16, v0
	v_fma_f32 v0, v65, v0, v14
	v_mul_f32_e32 v14, 0x3d372713, v0
	v_mul_f32_e32 v14, v0, v14
	v_fma_f32 v14, v0, v14, v0
	v_mul_f32_e32 v14, 0x3fcc422a, v14
	v_mul_f32_e32 v14, 0xbfb8aa3b, v14
	v_exp_f32_e32 v14, v14
	v_mfma_f32_16x16x32_bf16 v[2:5], v[22:25], v[2:5], v[18:21]
	v_add_f32_e32 v14, 1.0, v14
	s_nop 1
	v_div_scale_f32 v18, s[48:49], v14, v14, 1.0
	v_rcp_f32_e32 v19, v18
	s_nop 2
	v_fmac_f32_e32 v5, v65, v66
	v_fma_f32 v20, -v18, v19, 1.0
	v_fmac_f32_e32 v19, v20, v19
	v_div_scale_f32 v20, vcc, 1.0, v14, 1.0
	v_mul_f32_e32 v21, v20, v19
	v_fma_f32 v22, -v18, v21, v20
	v_fmac_f32_e32 v21, v22, v19
	v_fma_f32 v18, -v18, v21, v20
	v_div_fmas_f32 v18, v18, v19, v21
	v_div_fixup_f32 v14, v18, v14, 1.0
	v_mul_f32_e32 v0, v0, v14
	v_bfe_u32 v14, v0, 16, 1
	v_add3_u32 v14, v0, v14, s94
	global_load_ushort v18, v[60:61], off
	global_load_ushort v19, v[58:59], off
	global_load_ushort v20, v[56:57], off
	global_load_ushort v21, v[54:55], off
	global_load_ushort v22, v[52:53], off
	global_load_ushort v23, v[48:49], off
	global_load_ushort v0, v[46:47], off
	s_waitcnt vmcnt(0) lgkmcnt(0)
	v_lshlrev_b32_e32 v0, 16, v0
	global_store_short_d16_hi v[62:63], v14, off
	v_lshlrev_b32_e32 v14, 16, v18
	v_fma_f32 v14, v65, v14, v15
	v_mul_f32_e32 v15, 0x3d372713, v14
	v_mul_f32_e32 v15, v14, v15
	v_fma_f32 v15, v14, v15, v14
	v_mul_f32_e32 v15, 0x3fcc422a, v15
	v_mul_f32_e32 v15, 0xbfb8aa3b, v15
	v_exp_f32_e32 v15, v15
	v_fmac_f32_e32 v13, v65, v0
	v_mul_f32_e32 v0, 0x3d372713, v13
	v_mul_f32_e32 v0, v13, v0
	v_add_f32_e32 v15, 1.0, v15
	v_div_scale_f32 v18, s[48:49], v15, v15, 1.0
	v_rcp_f32_e32 v24, v18
	v_fma_f32 v0, v13, v0, v13
	v_mul_f32_e32 v0, 0x3fcc422a, v0
	v_mul_f32_e32 v0, 0xbfb8aa3b, v0
	v_fma_f32 v25, -v18, v24, 1.0
	v_fmac_f32_e32 v24, v25, v24
	v_div_scale_f32 v25, vcc, 1.0, v15, 1.0
	v_mul_f32_e32 v26, v25, v24
	v_fma_f32 v27, -v18, v26, v25
	v_fmac_f32_e32 v26, v27, v24
	v_fma_f32 v18, -v18, v26, v25
	v_div_fmas_f32 v18, v18, v24, v26
	v_div_fixup_f32 v15, v18, v15, 1.0
	v_mul_f32_e32 v14, v14, v15
	v_bfe_u32 v15, v14, 16, 1
	v_add3_u32 v14, v14, v15, s94
	global_store_short_d16_hi v[60:61], v14, off
	v_lshlrev_b32_e32 v14, 16, v19
	v_fma_f32 v14, v65, v14, v16
	v_mul_f32_e32 v15, 0x3d372713, v14
	v_mul_f32_e32 v15, v14, v15
	v_fma_f32 v15, v14, v15, v14
	v_mul_f32_e32 v15, 0x3fcc422a, v15
	v_mul_f32_e32 v15, 0xbfb8aa3b, v15
	v_exp_f32_e32 v15, v15
	v_exp_f32_e32 v0, v0
	v_add_f32_e32 v15, 1.0, v15
	v_div_scale_f32 v16, s[48:49], v15, v15, 1.0
	v_rcp_f32_e32 v18, v16
	v_add_f32_e32 v0, 1.0, v0
	v_fma_f32 v19, -v16, v18, 1.0
	v_fmac_f32_e32 v18, v19, v18
	v_div_scale_f32 v19, vcc, 1.0, v15, 1.0
	v_mul_f32_e32 v24, v19, v18
	v_fma_f32 v25, -v16, v24, v19
	v_fmac_f32_e32 v24, v25, v18
	v_fma_f32 v16, -v16, v24, v19
	v_div_fmas_f32 v16, v16, v18, v24
	v_div_fixup_f32 v15, v16, v15, 1.0
	v_mul_f32_e32 v14, v14, v15
	v_bfe_u32 v15, v14, 16, 1
	v_add3_u32 v14, v14, v15, s94
	global_store_short_d16_hi v[58:59], v14, off
	v_lshlrev_b32_e32 v14, 16, v20
	v_fmac_f32_e32 v17, v65, v14
	v_mul_f32_e32 v14, 0x3d372713, v17
	v_mul_f32_e32 v14, v17, v14
	v_fma_f32 v14, v17, v14, v17
	v_mul_f32_e32 v14, 0x3fcc422a, v14
	v_mul_f32_e32 v14, 0xbfb8aa3b, v14
	v_exp_f32_e32 v14, v14
	s_nop 0
	v_add_f32_e32 v14, 1.0, v14
	v_div_scale_f32 v15, s[48:49], v14, v14, 1.0
	v_rcp_f32_e32 v16, v15
	s_nop 0
	v_fma_f32 v18, -v15, v16, 1.0
	v_fmac_f32_e32 v16, v18, v16
	v_div_scale_f32 v18, vcc, 1.0, v14, 1.0
	v_mul_f32_e32 v19, v18, v16
	v_fma_f32 v20, -v15, v19, v18
; DI u16 f2bf(float x) { uint32_t u = __float_as_uint(x); u += 0x7fffu + ((u >> 16) & 1u); return (u16)(u >> 16); }
; DI float bf2f(u16 h) { return __uint_as_float(((uint32_t)h) << 16); }
; DI float geluf_(float v) { return v * sigmoidf_(1.5957691216f * (v + 0.044715f * v * v * v)); }
; DI void ssm_unit(const Params& p, int l, int g, int row0, int T, float& hr, float& hi, bool write_y, u16* tile) {
;     ...
;   for (int mt = 0; mt < 4; ++mt) {
;     if (mt < ntile) {
; #pragma unroll
;       for (int j = 0; j < 4; ++j) {
;         u16* up = ((u16*)(p.ws + WS_U)) + (size_t)(row0 + mt * 16 + fq * 4 + j) * 512 + g * 16 + fr;
;         const float y = ya[mt][j] + dsk * bf2f(uv[mt][j]);
;         *up = f2bf(geluf_(y));
;       }
	v_fmac_f32_e32 v19, v20, v16
	v_fma_f32 v15, -v15, v19, v18
	v_div_fmas_f32 v15, v15, v16, v19
	v_div_fixup_f32 v14, v15, v14, 1.0
	v_mul_f32_e32 v14, v17, v14
	v_bfe_u32 v15, v14, 16, 1
	v_add3_u32 v14, v14, v15, s94
	global_store_short_d16_hi v[56:57], v14, off
	v_lshlrev_b32_e32 v14, 16, v21
	v_fma_f32 v10, v65, v14, v10
	v_mul_f32_e32 v14, 0x3d372713, v10
	v_mul_f32_e32 v14, v10, v14
	v_fma_f32 v14, v10, v14, v10
	v_mul_f32_e32 v14, 0x3fcc422a, v14
	v_mul_f32_e32 v14, 0xbfb8aa3b, v14
	v_exp_f32_e32 v14, v14
	s_nop 0
	v_add_f32_e32 v14, 1.0, v14
	v_div_scale_f32 v15, s[48:49], v14, v14, 1.0
	v_rcp_f32_e32 v16, v15
	s_nop 0
	v_fma_f32 v17, -v15, v16, 1.0
	v_fmac_f32_e32 v16, v17, v16
	v_div_scale_f32 v17, vcc, 1.0, v14, 1.0
	v_mul_f32_e32 v18, v17, v16
	v_fma_f32 v19, -v15, v18, v17
	v_fmac_f32_e32 v18, v19, v16
	v_fma_f32 v15, -v15, v18, v17
	v_div_fmas_f32 v15, v15, v16, v18
	v_div_fixup_f32 v14, v15, v14, 1.0
	v_mul_f32_e32 v10, v10, v14
	v_bfe_u32 v14, v10, 16, 1
	v_add3_u32 v10, v10, v14, s94
	global_store_short_d16_hi v[54:55], v10, off
	v_lshlrev_b32_e32 v10, 16, v22
	v_fma_f32 v10, v65, v10, v11
	v_mul_f32_e32 v11, 0x3d372713, v10
	v_mul_f32_e32 v11, v10, v11
	v_fma_f32 v11, v10, v11, v10
	v_mul_f32_e32 v11, 0x3fcc422a, v11
	v_mul_f32_e32 v11, 0xbfb8aa3b, v11
	v_exp_f32_e32 v11, v11
	s_nop 0
	v_add_f32_e32 v11, 1.0, v11
	v_div_scale_f32 v14, s[48:49], v11, v11, 1.0
	v_rcp_f32_e32 v15, v14
	s_nop 0
	v_fma_f32 v16, -v14, v15, 1.0
	v_fmac_f32_e32 v15, v16, v15
	v_div_scale_f32 v16, vcc, 1.0, v11, 1.0
	v_mul_f32_e32 v17, v16, v15
	v_fma_f32 v18, -v14, v17, v16
	v_fmac_f32_e32 v17, v18, v15
	v_fma_f32 v14, -v14, v17, v16
	v_div_fmas_f32 v14, v14, v15, v17
	v_div_fixup_f32 v11, v14, v11, 1.0
	v_mul_f32_e32 v10, v10, v11
	v_bfe_u32 v11, v10, 16, 1
	v_add3_u32 v10, v10, v11, s94
	global_store_short_d16_hi v[52:53], v10, off
	v_lshlrev_b32_e32 v10, 16, v23
	v_fma_f32 v10, v65, v10, v12
	v_mul_f32_e32 v11, 0x3d372713, v10
	v_mul_f32_e32 v11, v10, v11
	v_fma_f32 v11, v10, v11, v10
	v_mul_f32_e32 v11, 0x3fcc422a, v11
	v_mul_f32_e32 v11, 0xbfb8aa3b, v11
	v_exp_f32_e32 v11, v11
	s_nop 0
	v_add_f32_e32 v11, 1.0, v11
	v_div_scale_f32 v12, s[48:49], v11, v11, 1.0
	v_rcp_f32_e32 v14, v12
	s_nop 0
	v_fma_f32 v15, -v12, v14, 1.0
	v_fmac_f32_e32 v14, v15, v14
	v_div_scale_f32 v15, vcc, 1.0, v11, 1.0
	v_mul_f32_e32 v16, v15, v14
	v_fma_f32 v17, -v12, v16, v15
	v_fmac_f32_e32 v16, v17, v14
	v_fma_f32 v12, -v12, v16, v15
	v_div_fmas_f32 v12, v12, v14, v16
	v_div_fixup_f32 v11, v12, v11, 1.0
	v_mul_f32_e32 v10, v10, v11
	v_bfe_u32 v11, v10, 16, 1
	v_add3_u32 v10, v10, v11, s94
	global_store_short_d16_hi v[48:49], v10, off
	v_div_scale_f32 v10, s[48:49], v0, v0, 1.0
	v_rcp_f32_e32 v11, v10
	s_nop 0
	v_fma_f32 v12, -v10, v11, 1.0
	v_fmac_f32_e32 v11, v12, v11
	v_div_scale_f32 v12, vcc, 1.0, v0, 1.0
	v_mul_f32_e32 v14, v12, v11
	v_fma_f32 v15, -v10, v14, v12
	v_fmac_f32_e32 v14, v15, v11
	v_fma_f32 v10, -v10, v14, v12
	v_div_fmas_f32 v10, v10, v11, v14
	v_div_fixup_f32 v0, v10, v0, 1.0
	v_mul_f32_e32 v0, v13, v0
	v_bfe_u32 v10, v0, 16, 1
	v_add3_u32 v0, v0, v10, s94
	global_store_short_d16_hi v[46:47], v0, off
	v_fma_f32 v0, v65, v73, v6
	v_mul_f32_e32 v6, 0x3d372713, v0
	v_mul_f32_e32 v6, v0, v6
	v_fma_f32 v6, v0, v6, v0
	v_mul_f32_e32 v6, 0x3fcc422a, v6
	v_mul_f32_e32 v6, 0xbfb8aa3b, v6
	v_exp_f32_e32 v6, v6
	s_nop 0
	v_add_f32_e32 v6, 1.0, v6
	v_div_scale_f32 v10, s[48:49], v6, v6, 1.0
	v_rcp_f32_e32 v11, v10
	s_nop 0
	v_fma_f32 v12, -v10, v11, 1.0
	v_fmac_f32_e32 v11, v12, v11
	v_div_scale_f32 v12, vcc, 1.0, v6, 1.0
	v_mul_f32_e32 v13, v12, v11
	v_fma_f32 v14, -v10, v13, v12
	v_fmac_f32_e32 v13, v14, v11
	v_fma_f32 v10, -v10, v13, v12
	v_div_fmas_f32 v10, v10, v11, v13
	v_div_fixup_f32 v6, v10, v6, 1.0
	v_mul_f32_e32 v0, v0, v6
	v_bfe_u32 v6, v0, 16, 1
	v_add3_u32 v0, v0, v6, s94
	global_store_short_d16_hi v[44:45], v0, off
	v_fma_f32 v0, v65, v72, v7
	v_mul_f32_e32 v6, 0x3d372713, v0
	v_mul_f32_e32 v6, v0, v6
	v_fma_f32 v6, v0, v6, v0
	v_mul_f32_e32 v6, 0x3fcc422a, v6
	v_mul_f32_e32 v6, 0xbfb8aa3b, v6
	v_exp_f32_e32 v6, v6
	s_nop 0
	v_add_f32_e32 v6, 1.0, v6
	v_div_scale_f32 v7, s[48:49], v6, v6, 1.0
	v_rcp_f32_e32 v10, v7
	s_nop 0
	v_fma_f32 v11, -v7, v10, 1.0
	v_fmac_f32_e32 v10, v11, v10
	v_div_scale_f32 v11, vcc, 1.0, v6, 1.0
	v_mul_f32_e32 v12, v11, v10
	v_fma_f32 v13, -v7, v12, v11
	v_fmac_f32_e32 v12, v13, v10
	v_fma_f32 v7, -v7, v12, v11
; DI u16 f2bf(float x) { uint32_t u = __float_as_uint(x); u += 0x7fffu + ((u >> 16) & 1u); return (u16)(u >> 16); }
; DI float bf2f(u16 h) { return __uint_as_float(((uint32_t)h) << 16); }
; DI float geluf_(float v) { return v * sigmoidf_(1.5957691216f * (v + 0.044715f * v * v * v)); }
; DI void ssm_unit(const Params& p, int l, int g, int row0, int T, float& hr, float& hi, bool write_y, u16* tile) {
;     ...
;   for (int mt = 0; mt < 4; ++mt) {
;     if (mt < ntile) {
; #pragma unroll
;       for (int j = 0; j < 4; ++j) {
;         u16* up = ((u16*)(p.ws + WS_U)) + (size_t)(row0 + mt * 16 + fq * 4 + j) * 512 + g * 16 + fr;
;         const float y = ya[mt][j] + dsk * bf2f(uv[mt][j]);
;         *up = f2bf(geluf_(y));
;       }
	v_div_fmas_f32 v7, v7, v10, v12
	v_div_fixup_f32 v6, v7, v6, 1.0
	v_mul_f32_e32 v0, v0, v6
	v_bfe_u32 v6, v0, 16, 1
	v_add3_u32 v0, v0, v6, s94
	global_store_short_d16_hi v[42:43], v0, off
	v_fma_f32 v0, v65, v71, v8
	v_mul_f32_e32 v6, 0x3d372713, v0
	v_mul_f32_e32 v6, v0, v6
	v_fma_f32 v6, v0, v6, v0
	v_mul_f32_e32 v6, 0x3fcc422a, v6
	v_mul_f32_e32 v6, 0xbfb8aa3b, v6
	v_exp_f32_e32 v6, v6
	s_nop 0
	v_add_f32_e32 v6, 1.0, v6
	v_div_scale_f32 v7, s[48:49], v6, v6, 1.0
	v_rcp_f32_e32 v8, v7
	s_nop 0
	v_fma_f32 v10, -v7, v8, 1.0
	v_fmac_f32_e32 v8, v10, v8
	v_div_scale_f32 v10, vcc, 1.0, v6, 1.0
	v_mul_f32_e32 v11, v10, v8
	v_fma_f32 v12, -v7, v11, v10
	v_fmac_f32_e32 v11, v12, v8
	v_fma_f32 v7, -v7, v11, v10
	v_div_fmas_f32 v7, v7, v8, v11
	v_div_fixup_f32 v6, v7, v6, 1.0
	v_mul_f32_e32 v0, v0, v6
	v_bfe_u32 v6, v0, 16, 1
	v_add3_u32 v0, v0, v6, s94
	global_store_short_d16_hi v[40:41], v0, off
	v_mul_f32_e32 v0, 0x3d372713, v9
	v_mul_f32_e32 v0, v9, v0
	v_fma_f32 v0, v9, v0, v9
	v_mul_f32_e32 v0, 0x3fcc422a, v0
	v_mul_f32_e32 v0, 0xbfb8aa3b, v0
	v_exp_f32_e32 v0, v0
	s_nop 0
	v_add_f32_e32 v0, 1.0, v0
	v_div_scale_f32 v6, s[48:49], v0, v0, 1.0
	v_rcp_f32_e32 v7, v6
	s_nop 0
	v_fma_f32 v8, -v6, v7, 1.0
	v_fmac_f32_e32 v7, v8, v7
	v_div_scale_f32 v8, vcc, 1.0, v0, 1.0
	v_mul_f32_e32 v10, v8, v7
	v_fma_f32 v11, -v6, v10, v8
	v_fmac_f32_e32 v10, v11, v7
	v_fma_f32 v6, -v6, v10, v8
	v_div_fmas_f32 v6, v6, v7, v10
	v_div_fixup_f32 v0, v6, v0, 1.0
	v_mul_f32_e32 v0, v9, v0
	v_bfe_u32 v6, v0, 16, 1
	v_add3_u32 v0, v0, v6, s94
	global_store_short_d16_hi v[38:39], v0, off
	v_fma_f32 v0, v65, v69, v2
	v_mul_f32_e32 v2, 0x3d372713, v0
	v_mul_f32_e32 v2, v0, v2
	v_fma_f32 v2, v0, v2, v0
	v_mul_f32_e32 v2, 0x3fcc422a, v2
	v_mul_f32_e32 v2, 0xbfb8aa3b, v2
	v_exp_f32_e32 v2, v2
	s_nop 0
	v_add_f32_e32 v2, 1.0, v2
	v_div_scale_f32 v6, s[48:49], v2, v2, 1.0
	v_rcp_f32_e32 v7, v6
	s_nop 0
	v_fma_f32 v8, -v6, v7, 1.0
	v_fmac_f32_e32 v7, v8, v7
	v_div_scale_f32 v8, vcc, 1.0, v2, 1.0
	v_mul_f32_e32 v9, v8, v7
	v_fma_f32 v10, -v6, v9, v8
	v_fmac_f32_e32 v9, v10, v7
	v_fma_f32 v6, -v6, v9, v8
	v_div_fmas_f32 v6, v6, v7, v9
	v_div_fixup_f32 v2, v6, v2, 1.0
	v_mul_f32_e32 v0, v0, v2
	v_bfe_u32 v2, v0, 16, 1
	v_add3_u32 v0, v0, v2, s94
	global_store_short_d16_hi v[36:37], v0, off
	v_fma_f32 v0, v65, v68, v3
	v_mul_f32_e32 v2, 0x3d372713, v0
	v_mul_f32_e32 v2, v0, v2
	v_fma_f32 v2, v0, v2, v0
	v_mul_f32_e32 v2, 0x3fcc422a, v2
	v_mul_f32_e32 v2, 0xbfb8aa3b, v2
	v_exp_f32_e32 v2, v2
	s_nop 0
	v_add_f32_e32 v2, 1.0, v2
	v_div_scale_f32 v3, s[48:49], v2, v2, 1.0
	v_rcp_f32_e32 v6, v3
	s_nop 0
	v_fma_f32 v7, -v3, v6, 1.0
	v_fmac_f32_e32 v6, v7, v6
	v_div_scale_f32 v7, vcc, 1.0, v2, 1.0
	v_mul_f32_e32 v8, v7, v6
	v_fma_f32 v9, -v3, v8, v7
	v_fmac_f32_e32 v8, v9, v6
	v_fma_f32 v3, -v3, v8, v7
	v_div_fmas_f32 v3, v3, v6, v8
	v_div_fixup_f32 v2, v3, v2, 1.0
	v_mul_f32_e32 v0, v0, v2
	v_bfe_u32 v2, v0, 16, 1
	v_add3_u32 v0, v0, v2, s94
	global_store_short_d16_hi v[34:35], v0, off
	v_fma_f32 v0, v65, v67, v4
	v_mul_f32_e32 v2, 0x3d372713, v0
	v_mul_f32_e32 v2, v0, v2
	v_fma_f32 v2, v0, v2, v0
	v_mul_f32_e32 v2, 0x3fcc422a, v2
	v_mul_f32_e32 v2, 0xbfb8aa3b, v2
	v_exp_f32_e32 v2, v2
	s_nop 0
	v_add_f32_e32 v2, 1.0, v2
	v_div_scale_f32 v3, s[48:49], v2, v2, 1.0
	v_rcp_f32_e32 v4, v3
	s_nop 0
	v_fma_f32 v6, -v3, v4, 1.0
	v_fmac_f32_e32 v4, v6, v4
	v_div_scale_f32 v6, vcc, 1.0, v2, 1.0
	v_mul_f32_e32 v7, v6, v4
	v_fma_f32 v8, -v3, v7, v6
	v_fmac_f32_e32 v7, v8, v4
	v_fma_f32 v3, -v3, v7, v6
	v_div_fmas_f32 v3, v3, v4, v7
	v_div_fixup_f32 v2, v3, v2, 1.0
	v_mul_f32_e32 v0, v0, v2
	v_bfe_u32 v2, v0, 16, 1
	v_add3_u32 v0, v0, v2, s94
	global_store_short_d16_hi v[32:33], v0, off
	v_mul_f32_e32 v0, 0x3d372713, v5
	v_mul_f32_e32 v0, v5, v0
	v_fma_f32 v0, v5, v0, v5
	v_mul_f32_e32 v0, 0x3fcc422a, v0
	v_mul_f32_e32 v0, 0xbfb8aa3b, v0
	v_exp_f32_e32 v0, v0
	s_nop 0
	v_add_f32_e32 v0, 1.0, v0
	v_div_scale_f32 v2, s[48:49], v0, v0, 1.0
	v_rcp_f32_e32 v3, v2
	s_nop 0
	v_fma_f32 v4, -v2, v3, 1.0
	v_fmac_f32_e32 v3, v4, v3
	v_div_scale_f32 v4, vcc, 1.0, v0, 1.0
	v_mul_f32_e32 v6, v4, v3
	v_fma_f32 v7, -v2, v6, v4
	v_fmac_f32_e32 v6, v7, v3
	v_fma_f32 v2, -v2, v6, v4
	v_div_fmas_f32 v2, v2, v3, v6
	v_div_fixup_f32 v0, v2, v0, 1.0
	v_mul_f32_e32 v0, v5, v0
	v_bfe_u32 v2, v0, 16, 1
	v_add3_u32 v0, v0, v2, s94
	global_store_short_d16_hi v[30:31], v0, off
	s_waitcnt lgkmcnt(0)
	s_branch .LBB0_203

; __device__ void attn_unit(const Params& p, bool smp, int b, int chunk, int h, char* lds) {
;     ...
;   auto gload = [&](int kt) {
; #pragma unroll
;     for (int i = 0; i < 2; ++i) {
;       rk[i] = *reinterpret_cast<const u32x4*>(Kb + (size_t)(kt * 64 + srow + i * 32) * 512 + sch * 8);
;       rv[i] = *reinterpret_cast<const u32x4*>(Vb + (size_t)(srow + i * 32) * Sv + kt * 64 + sch * 8);
;     }
;     mk = *reinterpret_cast<const u32x2*>(mrow + kt * 4);
;   };
;   auto lstore = [&](int buf) {
;     u16* sK = sbase + buf * STG;
;     u16* sV = sK + 64 * LR;
; #pragma unroll
;     for (int i = 0; i < 2; ++i) {
;       *reinterpret_cast<u32x4*>(sK + (srow + i * 32) * LR + sch * 8) = rk[i];
;       *reinterpret_cast<u32x4*>(sV + (srow + i * 32) * LR + sch * 8) = rv[i];
;     }
;   };
;   f32x4 Ot[4];
; #pragma unroll
;   for (int n = 0; n < 4; ++n) Ot[n] = f32x4{0.f, 0.f, 0.f, 0.f};
;   float mrun = -1e29f, lrun = 0.f;
;   gload(0);
;   __syncthreads();
;   lstore(0);
;   u32x2 mcur = mk;
;   if (ntile > 1) gload(1);
;   __syncthreads();
;   for (int kt = 0; kt < ntile; ++kt) {
;     const int cur = kt & 1;
;     const u32x2 mthis = mcur;
;     if (kt + 1 < ntile) { lstore(cur ^ 1); mcur = mk; }
;     if (kt + 2 < ntile) gload(kt + 2);
.LBB0_266:
	s_and_b32 s7, s6, 1
	s_xor_b32 s4, s7, 1
	s_mulk_i32 s4, 0x4800
	v_add_u32_e32 v0, s4, v58
	v_lshl_add_u64 v[2:3], s[36:37], 0, v[48:49]
	s_mov_b32 s4, 0x26c38000
	s_waitcnt vmcnt(0)
	ds_write_b128 v0, v[28:31]
	ds_write_b128 v0, v[32:35] offset:9216
	ds_write_b128 v0, v[36:39] offset:4608
	ds_write_b128 v0, v[40:43] offset:13824
	v_add_co_u32_e32 v28, vcc, s4, v2
	v_lshl_add_u64 v[36:37], s[36:37], 0, v[50:51]
	s_nop 0
	v_addc_co_u32_e32 v29, vcc, 0, v3, vcc
	s_mov_b32 s4, 0x2ad18000
	v_add_co_u32_e32 v32, vcc, s4, v36
	s_nop 1
	v_addc_co_u32_e32 v33, vcc, 0, v37, vcc
	v_add_co_u32_e32 v2, vcc, 0x26c40000, v2
	global_load_dwordx4 v[28:31], v[28:29], off
	s_nop 0
	global_load_dwordx4 v[32:35], v[32:33], off offset:256
	v_addc_co_u32_e32 v3, vcc, 0, v3, vcc
	v_add_co_u32_e32 v40, vcc, 0x2ad59000, v36
	s_nop 1
	v_addc_co_u32_e32 v41, vcc, 0, v37, vcc
	global_load_dwordx4 v[36:39], v[2:3], off
	s_nop 0
	global_load_dwordx4 v[40:43], v[40:41], off offset:256
	v_lshl_add_u64 v[2:3], s[36:37], 0, v[46:47]
	global_load_dwordx2 v[2:3], v[2:3], off
	s_and_saveexec_b64 s[4:5], s[2:3]
	s_cbranch_execz .LBB0_268
; DI f32x4 mfma16(bf16x8 a, bf16x8 b, f32x4 c) { return __builtin_amdgcn_mfma_f32_16x16x32_bf16(a, b, c, 0, 0, 0); }
; __device__ void attn_unit(const Params& p, bool smp, int b, int chunk, int h, char* lds) {
;     ...
;     if (active) {
;       const u16* sK = sbase + cur * STG;
;       const u16* sV = sK + 64 * LR;
;       f32x4 st[4];
; #pragma unroll
;       for (int n = 0; n < 4; ++n) {
;         f32x4 a = {0.f, 0.f, 0.f, 0.f};
; #pragma unroll
;         for (int ks = 0; ks < 2; ++ks) a = mfma16(*reinterpret_cast<const bf16x8*>(sK + (n * 16 + fr) * LR + ks * 32 + fq * 8), aq[ks], a);
;         st[n] = a;
;       }
;       float mx = -1e30f;
;       const int wlo = (int)(mthis[0] >> (fq * 4)), whi = (int)(mthis[1] >> (fq * 4));
; #pragma unroll
;       for (int n = 0; n < 4; ++n) {
; #pragma unroll
;         for (int j = 0; j < 4; ++j) {
;           const uint32_t sel = (uint32_t)__builtin_amdgcn_sbfe(n < 2 ? wlo : whi, (n & 1) * 16 + j, 1);
;           st[n][j] = __uint_as_float((__float_as_uint(st[n][j]) & sel) | (0xf149f2cau & ~sel));
;           mx = fmaxf(mx, st[n][j]);
;         }
;       }
;       mx = fmaxf(mx, __shfl_xor(mx, 16));
;       mx = fmaxf(mx, __shfl_xor(mx, 32));
;       const float mnew = fmaxf(mrun, mx);
;       const float alpha = __builtin_amdgcn_exp2f(mrun - mnew);
;       mrun = mnew;
;       float ps = 0.f;
; #pragma unroll
;       for (int n = 0; n < 4; ++n)
; #pragma unroll
;         for (int j = 0; j < 4; ++j) { st[n][j] = __builtin_amdgcn_exp2f(st[n][j] - mnew); ps += st[n][j]; }
;       lrun = lrun * alpha + ps;
; #pragma unroll
;       for (int n = 0; n < 4; ++n)
; #pragma unroll
;         for (int j = 0; j < 4; ++j) Ot[n][j] *= alpha;
; #pragma unroll
;       for (int ks = 0; ks < 2; ++ks) {
;         const bf16x8 pb = pack8_bf16(st[2 * ks][0], st[2 * ks][1], st[2 * ks][2], st[2 * ks][3],
;                                      st[2 * ks + 1][0], st[2 * ks + 1][1], st[2 * ks + 1][2], st[2 * ks + 1][3]);
; #pragma unroll
;         for (int dt = 0; dt < 4; ++dt) {
;           const u16* vr = sV + (dt * 16 + fr) * LR + ks * 32 + fq * 4;
;           const u32x2 v0 = *reinterpret_cast<const u32x2*>(vr), v1 = *reinterpret_cast<const u32x2*>(vr + 16);
;           const u32x4 vv = {v0[0], v0[1], v1[0], v1[1]};
;           Ot[dt] = mfma16(__builtin_bit_cast(bf16x8, vv), pb, Ot[dt]);
;         }
;       }
	s_mulk_i32 s7, 0x4800
	v_lshlrev_b32_e32 v0, 1, v59
	v_add3_u32 v86, v60, s7, v0
	v_add_u32_e32 v87, v86, v61
	ds_read_b128 v[66:69], v86
	ds_read_b128 v[88:91], v86 offset:64
	ds_read_b128 v[70:73], v86 offset:2304
	ds_read_b128 v[92:95], v86 offset:2368
	ds_read_b128 v[74:77], v86 offset:4608
	ds_read_b128 v[96:99], v86 offset:4672
	ds_read_b128 v[78:81], v86 offset:6912
	ds_read_b128 v[100:103], v86 offset:6976
	ds_read_b64 v[104:105], v87 offset:9216
	ds_read_b64 v[106:107], v87 offset:9248
	v_lshrrev_b32_e32 v0, v57, v52
	v_lshrrev_b32_e32 v53, v57, v53
	s_waitcnt lgkmcnt(8)
	v_mfma_f32_16x16x32_bf16 v[66:69], v[66:69], v[20:23], 0
	ds_read_b64 v[108:109], v87 offset:11520
	ds_read_b64 v[110:111], v87 offset:11552
	ds_read_b64 v[112:113], v87 offset:13824
	ds_read_b64 v[114:115], v87 offset:13856
	v_mfma_f32_16x16x32_bf16 v[66:69], v[88:91], v[16:19], v[66:69]
	s_waitcnt lgkmcnt(10)
	v_mfma_f32_16x16x32_bf16 v[70:73], v[70:73], v[20:23], 0
	ds_read_b64 v[116:117], v87 offset:16128
	ds_read_b64 v[118:119], v87 offset:16160
	ds_read_b64 v[122:123], v87 offset:9280
	ds_read_b64 v[124:125], v87 offset:9312
	v_mfma_f32_16x16x32_bf16 v[70:73], v[92:95], v[16:19], v[70:73]
	s_waitcnt lgkmcnt(12)
	v_mfma_f32_16x16x32_bf16 v[74:77], v[74:77], v[20:23], 0
	ds_read_b64 v[126:127], v87 offset:11584
	ds_read_b64 v[128:129], v87 offset:11616
	v_mfma_f32_16x16x32_bf16 v[74:77], v[96:99], v[16:19], v[74:77]
	s_waitcnt lgkmcnt(12)
	v_mfma_f32_16x16x32_bf16 v[78:81], v[78:81], v[20:23], 0
	ds_read_b64 v[130:131], v87 offset:13888
	ds_read_b64 v[132:133], v87 offset:13920
	v_mfma_f32_16x16x32_bf16 v[78:81], v[100:103], v[16:19], v[78:81]
	s_waitcnt lgkmcnt(12)
	ds_read_b64 v[82:83], v87 offset:16192
	ds_read_b64 v[84:85], v87 offset:16224
	v_bfe_i32 v134, v0, 0, 1
	v_bfe_i32 v135, v0, 1, 1
	v_bitop3_b32 v66, v66, s87, v134 bitop3:0xe4
	v_bitop3_b32 v67, v67, s87, v135 bitop3:0xe4
	v_bfe_i32 v134, v0, 2, 1
	v_bfe_i32 v135, v0, 3, 1
	v_bitop3_b32 v68, v68, s87, v134 bitop3:0xe4
	v_bitop3_b32 v69, v69, s87, v135 bitop3:0xe4
	v_max3_f32 v136, v66, v67, v68
	v_max_f32_e32 v136, v136, v69
	v_bfe_i32 v134, v0, 16, 1
	v_bfe_i32 v135, v0, 17, 1
	v_bitop3_b32 v70, v70, s87, v134 bitop3:0xe4
	v_bitop3_b32 v71, v71, s87, v135 bitop3:0xe4
	v_bfe_i32 v134, v0, 18, 1
	v_bfe_i32 v135, v0, 19, 1
	v_bitop3_b32 v72, v72, s87, v134 bitop3:0xe4
	v_bitop3_b32 v73, v73, s87, v135 bitop3:0xe4
	v_max3_f32 v136, v136, v70, v71
	v_max3_f32 v136, v136, v72, v73
	v_bfe_i32 v134, v53, 0, 1
	v_bfe_i32 v135, v53, 1, 1
	v_bitop3_b32 v74, v74, s87, v134 bitop3:0xe4
	v_bitop3_b32 v75, v75, s87, v135 bitop3:0xe4
	v_bfe_i32 v134, v53, 2, 1
	v_bfe_i32 v135, v53, 3, 1
	v_bitop3_b32 v76, v76, s87, v134 bitop3:0xe4
	v_bitop3_b32 v77, v77, s87, v135 bitop3:0xe4
	v_max3_f32 v136, v136, v74, v75
	v_max3_f32 v136, v136, v76, v77
	v_bfe_i32 v134, v53, 16, 1
	v_bfe_i32 v135, v53, 17, 1
	v_bitop3_b32 v78, v78, s87, v134 bitop3:0xe4
	v_bitop3_b32 v79, v79, s87, v135 bitop3:0xe4
	v_bfe_i32 v134, v53, 18, 1
	v_bfe_i32 v135, v53, 19, 1
	v_bitop3_b32 v80, v80, s87, v134 bitop3:0xe4
	v_bitop3_b32 v81, v81, s87, v135 bitop3:0xe4
	v_max3_f32 v136, v136, v78, v79
	v_max3_f32 v136, v136, v80, v81
	v_mov_b32_e32 v135, v136
	s_nop 1
	v_permlane32_swap_b32_e32 v135, v136
	v_max_f32_e32 v136, v135, v136
	v_mov_b32_e32 v135, v136
	s_nop 1
	v_permlane16_swap_b32_e32 v135, v136
	v_max3_f32 v134, v62, v135, v136
	v_sub_f32_e32 v52, v62, v134
	v_exp_f32_e32 v52, v52
	v_mov_b32_e32 v62, v134
	v_sub_f32_e32 v66, v66, v134
	v_exp_f32_e32 v66, v66
	v_sub_f32_e32 v67, v67, v134
	v_exp_f32_e32 v67, v67
	v_add_f32_e32 v135, 0, v66
	v_sub_f32_e32 v68, v68, v134
	v_exp_f32_e32 v68, v68
	v_add_f32_e32 v135, v67, v135
	v_sub_f32_e32 v69, v69, v134
	v_exp_f32_e32 v69, v69
	v_add_f32_e32 v135, v68, v135
	v_pk_mul_f32 v[6:7], v[6:7], v[52:53] op_sel_hi:[1,0]
	v_pk_mul_f32 v[4:5], v[4:5], v[52:53] op_sel_hi:[1,0]
	v_sub_f32_e32 v70, v70, v134
	v_exp_f32_e32 v70, v70
	v_add_f32_e32 v135, v69, v135
	v_sub_f32_e32 v71, v71, v134
	v_exp_f32_e32 v71, v71
	v_add_f32_e32 v135, v70, v135
	v_pk_mul_f32 v[14:15], v[14:15], v[52:53] op_sel_hi:[1,0]
	v_pk_mul_f32 v[12:13], v[12:13], v[52:53] op_sel_hi:[1,0]
	v_sub_f32_e32 v72, v72, v134
	v_exp_f32_e32 v72, v72
	v_add_f32_e32 v135, v71, v135
	v_sub_f32_e32 v73, v73, v134
	v_exp_f32_e32 v73, v73
	v_add_f32_e32 v135, v72, v135
	v_pk_mul_f32 v[10:11], v[10:11], v[52:53] op_sel_hi:[1,0]
	v_pk_mul_f32 v[8:9], v[8:9], v[52:53] op_sel_hi:[1,0]
	v_sub_f32_e32 v74, v74, v134
	v_exp_f32_e32 v74, v74
	v_add_f32_e32 v135, v73, v135
	v_sub_f32_e32 v75, v75, v134
	v_exp_f32_e32 v75, v75
	v_add_f32_e32 v135, v74, v135
	v_pk_mul_f32 v[26:27], v[26:27], v[52:53] op_sel_hi:[1,0]
	v_pk_mul_f32 v[24:25], v[24:25], v[52:53] op_sel_hi:[1,0]
	v_sub_f32_e32 v76, v76, v134
	v_exp_f32_e32 v76, v76
	v_add_f32_e32 v135, v75, v135
	v_sub_f32_e32 v77, v77, v134
	v_exp_f32_e32 v77, v77
	v_add_f32_e32 v135, v76, v135
	v_sub_f32_e32 v78, v78, v134
	v_exp_f32_e32 v78, v78
	v_add_f32_e32 v135, v77, v135
	v_sub_f32_e32 v79, v79, v134
	v_exp_f32_e32 v79, v79
	v_add_f32_e32 v135, v78, v135
	v_sub_f32_e32 v80, v80, v134
	v_exp_f32_e32 v80, v80
	v_add_f32_e32 v135, v79, v135
	v_sub_f32_e32 v81, v81, v134
	v_exp_f32_e32 v81, v81
	v_add_f32_e32 v135, v80, v135
	v_cvt_pk_bf16_f32 v88, v66, v67
	v_cvt_pk_bf16_f32 v89, v68, v69
	v_cvt_pk_bf16_f32 v90, v70, v71
	v_cvt_pk_bf16_f32 v91, v72, v73
	v_add_f32_e32 v135, v81, v135
	v_cvt_pk_bf16_f32 v92, v74, v75
	v_cvt_pk_bf16_f32 v93, v76, v77
	v_cvt_pk_bf16_f32 v94, v78, v79
	v_cvt_pk_bf16_f32 v95, v80, v81
	v_fmac_f32_e32 v135, v56, v52
	s_waitcnt lgkmcnt(0)
	v_mov_b32_e32 v56, v135
	v_mfma_f32_16x16x32_bf16 v[4:7], v[104:107], v[88:91], v[4:7]
	v_mfma_f32_16x16x32_bf16 v[12:15], v[108:111], v[88:91], v[12:15]
	v_mfma_f32_16x16x32_bf16 v[8:11], v[112:115], v[88:91], v[8:11]
	v_mfma_f32_16x16x32_bf16 v[24:27], v[116:119], v[88:91], v[24:27]
	v_mfma_f32_16x16x32_bf16 v[4:7], v[122:125], v[92:95], v[4:7]
	v_mfma_f32_16x16x32_bf16 v[12:15], v[126:129], v[92:95], v[12:15]
	v_mfma_f32_16x16x32_bf16 v[8:11], v[130:133], v[92:95], v[8:11]
	v_mfma_f32_16x16x32_bf16 v[24:27], v[82:85], v[92:95], v[24:27]

;   DI bool next(int& mt, int& nt) {
;     for (;;) {
;       const int s = j + nb * k; ++k;
;       const int g = s / (2 * NN), r = s - g * (2 * NN);
;       if (g * 2 >= cnt) return false;
;       const int i = g * 2 + (r & 1);
;       if (i >= cnt) continue;
;       mt = x + 8 * i; nt = r >> 1; return true;
;     }
.LBB0_910:
	v_readlane_b32 s4, v236, 9
	s_mul_i32 s6, s60, s4
	v_readlane_b32 s4, v236, 20
	s_add_i32 s6, s6, s4
	s_mul_hi_u32 s4, s6, 0x8d3dcb09
	s_lshr_b32 s7, s4, 6
	s_lshl_b32 s4, s7, 2
	v_readlane_b32 s49, v236, 10
	s_cmp_ge_u32 s4, s49
	v_readlane_b32 s5, v236, 21
	s_cbranch_scc1 .LBB0_914
	s_and_b32 s5, s6, 3
	s_or_b32 s48, s4, s5
	s_cmp_ge_u32 s48, s49
	s_mov_b64 s[4:5], 0
	s_cbranch_scc1 .LBB0_913
	s_mul_i32 s2, s7, 0xffffff8c
	s_add_i32 s2, s2, s6
	s_ashr_i32 s63, s2, 2
	s_lshl_b32 s2, s48, 3
	v_readlane_b32 s3, v236, 44
	s_or_b32 s50, s2, s3
	s_mov_b64 s[2:3], -1
	s_branch .LBB0_915

; DI int tidx() { int t = threadIdx.x; asm volatile("" : "+v"(t)); return t; }
; __device__ void phase_prep(const Params& p, char* lds) {
;     ...
;   for (int u = blockIdx.x; u < 192; u += gridDim.x) {
;     const int l = u / 96, cg_ = u % 96;
;     const int col = tidx() & 31, ks = tidx() >> 5;
;     float acc[24];
; #pragma unroll
;     for (int r = 0; r < 24; ++r) acc[r] = 0.f;
;     const float* wm = p.w_mod + (size_t)l * 1024 * 3072 + cg_ * 32 + col;
;     for (int k = ks * 128; k < ks * 128 + 128; ++k) {
;       const float w = wm[(size_t)k * 3072];
; #pragma unroll
;       for (int r = 0; r < 24; ++r) {
;         const float c = r < 8 ? p.c_prompt[r * 1024 + k] : p.c_sample[(r - 8) * 1024 + k];
.LBB0_1590:
	s_mul_hi_i32 s0, s8, 0x2aaaaaab
	s_lshr_b32 s1, s0, 31
	s_ashr_i32 s0, s0, 4
	s_add_i32 s9, s0, s1
	s_mul_i32 s0, s9, 0x60
	s_sub_i32 s0, s8, s0
	v_mov_b32_e32 v0, v154
	v_mov_b32_e32 v2, v154
	s_lshl_b32 s0, s0, 5
	s_ashr_i32 s1, s0, 31
	s_waitcnt vmcnt(0)
	v_ashrrev_i32_e32 v62, 5, v2
	s_mul_i32 s4, s9, 0xc00000
	v_lshlrev_b32_e32 v30, 7, v62
	s_lshl_b64 s[2:3], s[0:1], 2
	s_mul_hi_i32 s5, s9, 0xc00000
	v_ashrrev_i32_e32 v31, 31, v30
	s_add_u32 s4, s2, s4
	v_lshlrev_b64 v[34:35], 2, v[30:31]
	s_addc_u32 s5, s3, s5
	v_lshl_add_u64 v[36:37], s[18:19], 0, v[34:35]
	v_lshl_add_u64 v[38:39], s[12:13], 0, v[34:35]
	v_mov_b64_e32 v[34:35], s[4:5]
	v_and_b32_e32 v63, 31, v0
	v_add_u32_e32 v2, 0x3c00, v30
	v_add_u32_e32 v4, 0x3800, v30
	v_add_u32_e32 v6, 0x3400, v30
	v_add_u32_e32 v8, 0x3000, v30
	v_add_u32_e32 v10, 0x2c00, v30
	v_add_u32_e32 v12, 0x2800, v30
	v_add_u32_e32 v14, 0x2400, v30
	v_add_u32_e32 v16, 0x2000, v30
	v_add_u32_e32 v18, 0x1c00, v30
	v_add_u32_e32 v20, 0x1800, v30
	v_add_u32_e32 v22, 0x1400, v30
	v_add_u32_e32 v24, 0x1000, v30
	v_add_u32_e32 v26, 0xc00, v30
	v_add_u32_e32 v28, 0x800, v30
	v_add_u32_e32 v32, 0x400, v30
	v_mad_i64_i32 v[30:31], s[4:5], v30, s88, v[34:35]
	v_lshl_or_b32 v30, v63, 2, v30
	v_ashrrev_i32_e32 v3, 31, v2
	v_ashrrev_i32_e32 v5, 31, v4
	v_ashrrev_i32_e32 v7, 31, v6
	v_ashrrev_i32_e32 v9, 31, v8
	v_ashrrev_i32_e32 v11, 31, v10
	v_ashrrev_i32_e32 v13, 31, v12
	v_ashrrev_i32_e32 v15, 31, v14
	v_ashrrev_i32_e32 v17, 31, v16
	v_ashrrev_i32_e32 v19, 31, v18
	v_ashrrev_i32_e32 v21, 31, v20
	v_ashrrev_i32_e32 v23, 31, v22
	v_ashrrev_i32_e32 v25, 31, v24
	v_ashrrev_i32_e32 v27, 31, v26
	v_ashrrev_i32_e32 v29, 31, v28
	v_ashrrev_i32_e32 v33, 31, v32
	v_lshl_add_u64 v[48:49], s[14:15], 0, v[30:31]
	v_mov_b32_e32 v30, 0
	v_lshl_add_u64 v[2:3], v[2:3], 2, s[18:19]
	v_lshl_add_u64 v[4:5], v[4:5], 2, s[18:19]
	v_lshl_add_u64 v[6:7], v[6:7], 2, s[18:19]
	v_lshl_add_u64 v[8:9], v[8:9], 2, s[18:19]
	v_lshl_add_u64 v[10:11], v[10:11], 2, s[18:19]
	v_lshl_add_u64 v[12:13], v[12:13], 2, s[18:19]
	v_lshl_add_u64 v[14:15], v[14:15], 2, s[18:19]
	v_lshl_add_u64 v[16:17], v[16:17], 2, s[18:19]
	v_lshl_add_u64 v[18:19], v[18:19], 2, s[18:19]
	v_lshl_add_u64 v[20:21], v[20:21], 2, s[18:19]
	v_lshl_add_u64 v[22:23], v[22:23], 2, s[18:19]
	v_lshl_add_u64 v[24:25], v[24:25], 2, s[18:19]
	v_lshl_add_u64 v[26:27], v[26:27], 2, s[18:19]
	v_lshl_add_u64 v[28:29], v[28:29], 2, s[18:19]
	v_lshl_add_u64 v[32:33], v[32:33], 2, s[18:19]
	s_mov_b64 s[4:5], 0
	v_mov_b32_e32 v31, v30
	v_mov_b32_e32 v34, v30
	v_mov_b32_e32 v35, v30
	v_mov_b32_e32 v40, v30
	v_mov_b32_e32 v41, v30
	v_mov_b32_e32 v42, v30
	v_mov_b32_e32 v43, v30
	v_mov_b32_e32 v44, v30
	v_mov_b32_e32 v45, v30
	v_mov_b32_e32 v46, v30
	s_waitcnt lgkmcnt(0)
	v_mov_b32_e32 v47, v30
	v_mov_b32_e32 v50, v30
	v_mov_b32_e32 v51, v30
	v_mov_b32_e32 v52, v30
	v_mov_b32_e32 v53, v30
	v_mov_b32_e32 v54, v30
	v_mov_b32_e32 v55, v30
	v_mov_b32_e32 v56, v30
	v_mov_b32_e32 v57, v30
	v_mov_b32_e32 v58, v30
	v_mov_b32_e32 v59, v30
	v_mov_b32_e32 v60, v30
	v_mov_b32_e32 v61, v30
	v_and_b32_e32 v68, 15, v154
	v_xor_b32_e32 v69, 1, v68
	v_cmp_gt_u32_e32 vcc, 8, v69
	v_add_u32_e32 v70, -8, v69
	s_nop 1
	v_cndmask_b32_e32 v70, v70, v69, vcc
	v_lshlrev_b32_e32 v70, 12, v70
	v_cndmask_b32_e32 v64, v36, v38, vcc
	v_cndmask_b32_e32 v65, v37, v39, vcc
	v_mov_b32_e32 v71, 0
	v_lshl_add_u64 v[64:65], v[64:65], 0, v[70:71]
	v_and_b32_e32 v68, 7, v68
	v_or_b32_e32 v68, 16, v68
	v_xor_b32_e32 v68, 1, v68
	v_add_u32_e32 v68, -8, v68
	v_lshlrev_b32_e32 v70, 12, v68
	v_lshl_add_u64 v[66:67], v[36:37], 0, v[70:71]
.Lmod_kloop:
	s_mov_b64 s[10:11], 0x3000
	v_lshl_add_u64 v[68:69], v[64:65], 0, s[4:5]
	v_lshl_add_u64 v[70:71], v[66:67], 0, s[4:5]
	global_load_dwordx4 v[76:79], v[68:69], off
	global_load_dwordx4 v[80:83], v[70:71], off
	global_load_dword v84, v[48:49], off
	v_lshl_add_u64 v[48:49], v[48:49], 0, s[10:11]
	global_load_dword v85, v[48:49], off
	v_lshl_add_u64 v[48:49], v[48:49], 0, s[10:11]
	global_load_dword v86, v[48:49], off
	v_lshl_add_u64 v[48:49], v[48:49], 0, s[10:11]
	global_load_dword v87, v[48:49], off
	v_lshl_add_u64 v[48:49], v[48:49], 0, s[10:11]
	s_add_u32 s4, s4, 16
	s_addc_u32 s5, s5, 0
	s_waitcnt vmcnt(0)
; DI float sigmoidf_(float x) { return 1.f / (1.f + __expf(-x)); }
; DI float siluf_(float x) { return x * sigmoidf_(x); }
; __device__ void phase_prep(const Params& p, char* lds) {
;     ...
;     for (int k = ks * 128; k < ks * 128 + 128; ++k) {
;       const float w = wm[(size_t)k * 3072];
; #pragma unroll
;       for (int r = 0; r < 24; ++r) {
;         const float c = r < 8 ? p.c_prompt[r * 1024 + k] : p.c_sample[(r - 8) * 1024 + k];
;         acc[r] = fmaf(siluf_(c), w, acc[r]);
;       }
	v_mul_f32_e32 v68, 0xbfb8aa3b, v76
	v_exp_f32_e32 v68, v68
	s_nop 0
	v_add_f32_e32 v68, 1.0, v68
	v_div_scale_f32 v69, s[10:11], v68, v68, 1.0
	v_rcp_f32_e32 v70, v69
	s_nop 0
	v_fma_f32 v71, -v69, v70, 1.0
	v_fmac_f32_e32 v70, v71, v70
	v_div_scale_f32 v71, vcc, 1.0, v68, 1.0
	v_mul_f32_e32 v72, v71, v70
	v_fma_f32 v73, -v69, v72, v71
	v_fmac_f32_e32 v72, v73, v70
	v_fma_f32 v69, -v69, v72, v71
	v_div_fmas_f32 v69, v69, v70, v72
	v_div_fixup_f32 v68, v69, v68, 1.0
	v_mul_f32_e32 v76, v76, v68
	v_mul_f32_e32 v68, 0xbfb8aa3b, v80
	v_exp_f32_e32 v68, v68
	s_nop 0
	v_add_f32_e32 v68, 1.0, v68
	v_div_scale_f32 v69, s[10:11], v68, v68, 1.0
	v_rcp_f32_e32 v70, v69
	s_nop 0
	v_fma_f32 v71, -v69, v70, 1.0
	v_fmac_f32_e32 v70, v71, v70
	v_div_scale_f32 v71, vcc, 1.0, v68, 1.0
	v_mul_f32_e32 v72, v71, v70
	v_fma_f32 v73, -v69, v72, v71
	v_fmac_f32_e32 v72, v73, v70
	v_fma_f32 v69, -v69, v72, v71
	v_div_fmas_f32 v69, v69, v70, v72
	v_div_fixup_f32 v68, v69, v68, 1.0
	v_mul_f32_e32 v80, v80, v68
	v_mul_f32_e32 v68, 0xbfb8aa3b, v77
	v_exp_f32_e32 v68, v68
	s_nop 0
	v_add_f32_e32 v68, 1.0, v68
	v_div_scale_f32 v69, s[10:11], v68, v68, 1.0
	v_rcp_f32_e32 v70, v69
	s_nop 0
	v_fma_f32 v71, -v69, v70, 1.0
	v_fmac_f32_e32 v70, v71, v70
	v_div_scale_f32 v71, vcc, 1.0, v68, 1.0
	v_mul_f32_e32 v72, v71, v70
	v_fma_f32 v73, -v69, v72, v71
	v_fmac_f32_e32 v72, v73, v70
	v_fma_f32 v69, -v69, v72, v71
	v_div_fmas_f32 v69, v69, v70, v72
	v_div_fixup_f32 v68, v69, v68, 1.0
	v_mul_f32_e32 v77, v77, v68
	v_mul_f32_e32 v68, 0xbfb8aa3b, v81
	v_exp_f32_e32 v68, v68
	s_nop 0
	v_add_f32_e32 v68, 1.0, v68
	v_div_scale_f32 v69, s[10:11], v68, v68, 1.0
	v_rcp_f32_e32 v70, v69
	s_nop 0
	v_fma_f32 v71, -v69, v70, 1.0
	v_fmac_f32_e32 v70, v71, v70
	v_div_scale_f32 v71, vcc, 1.0, v68, 1.0
	v_mul_f32_e32 v72, v71, v70
	v_fma_f32 v73, -v69, v72, v71
	v_fmac_f32_e32 v72, v73, v70
	v_fma_f32 v69, -v69, v72, v71
	v_div_fmas_f32 v69, v69, v70, v72
	v_div_fixup_f32 v68, v69, v68, 1.0
	v_mul_f32_e32 v81, v81, v68
	v_mul_f32_e32 v68, 0xbfb8aa3b, v78
	v_exp_f32_e32 v68, v68
	s_nop 0
	v_add_f32_e32 v68, 1.0, v68
	v_div_scale_f32 v69, s[10:11], v68, v68, 1.0
	v_rcp_f32_e32 v70, v69
	s_nop 0
	v_fma_f32 v71, -v69, v70, 1.0
	v_fmac_f32_e32 v70, v71, v70
	v_div_scale_f32 v71, vcc, 1.0, v68, 1.0
	v_mul_f32_e32 v72, v71, v70
	v_fma_f32 v73, -v69, v72, v71
	v_fmac_f32_e32 v72, v73, v70
	v_fma_f32 v69, -v69, v72, v71
	v_div_fmas_f32 v69, v69, v70, v72
	v_div_fixup_f32 v68, v69, v68, 1.0
	v_mul_f32_e32 v78, v78, v68
	v_mul_f32_e32 v68, 0xbfb8aa3b, v82
	v_exp_f32_e32 v68, v68
	s_nop 0
	v_add_f32_e32 v68, 1.0, v68
	v_div_scale_f32 v69, s[10:11], v68, v68, 1.0
	v_rcp_f32_e32 v70, v69
	s_nop 0
	v_fma_f32 v71, -v69, v70, 1.0
	v_fmac_f32_e32 v70, v71, v70
	v_div_scale_f32 v71, vcc, 1.0, v68, 1.0
	v_mul_f32_e32 v72, v71, v70
	v_fma_f32 v73, -v69, v72, v71
	v_fmac_f32_e32 v72, v73, v70
	v_fma_f32 v69, -v69, v72, v71
	v_div_fmas_f32 v69, v69, v70, v72
	v_div_fixup_f32 v68, v69, v68, 1.0
	v_mul_f32_e32 v82, v82, v68
	v_mul_f32_e32 v68, 0xbfb8aa3b, v79
	v_exp_f32_e32 v68, v68
	s_nop 0
	v_add_f32_e32 v68, 1.0, v68
	v_div_scale_f32 v69, s[10:11], v68, v68, 1.0
	v_rcp_f32_e32 v70, v69
	s_nop 0
	v_fma_f32 v71, -v69, v70, 1.0
	v_fmac_f32_e32 v70, v71, v70
	v_div_scale_f32 v71, vcc, 1.0, v68, 1.0
	v_mul_f32_e32 v72, v71, v70
	v_fma_f32 v73, -v69, v72, v71
	v_fmac_f32_e32 v72, v73, v70
	v_fma_f32 v69, -v69, v72, v71
	v_div_fmas_f32 v69, v69, v70, v72
	v_div_fixup_f32 v68, v69, v68, 1.0
	v_mul_f32_e32 v79, v79, v68
	v_mul_f32_e32 v68, 0xbfb8aa3b, v83
	v_exp_f32_e32 v68, v68
	s_nop 0
	v_add_f32_e32 v68, 1.0, v68
	v_div_scale_f32 v69, s[10:11], v68, v68, 1.0
	v_rcp_f32_e32 v70, v69
	s_nop 0
	v_fma_f32 v71, -v69, v70, 1.0
	v_fmac_f32_e32 v70, v71, v70
	v_div_scale_f32 v71, vcc, 1.0, v68, 1.0
	v_mul_f32_e32 v72, v71, v70
	v_fma_f32 v73, -v69, v72, v71
	v_fmac_f32_e32 v72, v73, v70
	v_fma_f32 v69, -v69, v72, v71
	v_div_fmas_f32 v69, v69, v70, v72
	v_div_fixup_f32 v68, v69, v68, 1.0
	v_mul_f32_e32 v83, v83, v68
	v_fmac_f32_dpp v60, v76, v84 row_newbcast:0 row_mask:0xf bank_mask:0xf
	v_fmac_f32_dpp v61, v76, v84 row_newbcast:1 row_mask:0xf bank_mask:0xf
	v_fmac_f32_dpp v58, v76, v84 row_newbcast:2 row_mask:0xf bank_mask:0xf
	v_fmac_f32_dpp v59, v76, v84 row_newbcast:3 row_mask:0xf bank_mask:0xf
	v_fmac_f32_dpp v56, v76, v84 row_newbcast:4 row_mask:0xf bank_mask:0xf
	v_fmac_f32_dpp v57, v76, v84 row_newbcast:5 row_mask:0xf bank_mask:0xf
	v_fmac_f32_dpp v54, v76, v84 row_newbcast:6 row_mask:0xf bank_mask:0xf
	v_fmac_f32_dpp v55, v76, v84 row_newbcast:7 row_mask:0xf bank_mask:0xf
	v_fmac_f32_dpp v52, v76, v84 row_newbcast:8 row_mask:0xf bank_mask:0xf
	v_fmac_f32_dpp v53, v76, v84 row_newbcast:9 row_mask:0xf bank_mask:0xf
	v_fmac_f32_dpp v50, v76, v84 row_newbcast:10 row_mask:0xf bank_mask:0xf
	v_fmac_f32_dpp v51, v76, v84 row_newbcast:11 row_mask:0xf bank_mask:0xf
	v_fmac_f32_dpp v46, v76, v84 row_newbcast:12 row_mask:0xf bank_mask:0xf
	v_fmac_f32_dpp v47, v76, v84 row_newbcast:13 row_mask:0xf bank_mask:0xf
	v_fmac_f32_dpp v44, v76, v84 row_newbcast:14 row_mask:0xf bank_mask:0xf
	v_fmac_f32_dpp v45, v76, v84 row_newbcast:15 row_mask:0xf bank_mask:0xf
	v_fmac_f32_dpp v42, v80, v84 row_newbcast:0 row_mask:0xf bank_mask:0xf
	v_fmac_f32_dpp v43, v80, v84 row_newbcast:1 row_mask:0xf bank_mask:0xf
	v_fmac_f32_dpp v40, v80, v84 row_newbcast:2 row_mask:0xf bank_mask:0xf
	v_fmac_f32_dpp v41, v80, v84 row_newbcast:3 row_mask:0xf bank_mask:0xf
	v_fmac_f32_dpp v34, v80, v84 row_newbcast:4 row_mask:0xf bank_mask:0xf
	v_fmac_f32_dpp v35, v80, v84 row_newbcast:5 row_mask:0xf bank_mask:0xf
	v_fmac_f32_dpp v30, v80, v84 row_newbcast:6 row_mask:0xf bank_mask:0xf
; DI float siluf_(float x) { return x * sigmoidf_(x); }
; DI int tidx() { int t = threadIdx.x; asm volatile("" : "+v"(t)); return t; }
; __device__ void phase_prep(const Params& p, char* lds) {
;     ...
;     for (int k = ks * 128; k < ks * 128 + 128; ++k) {
;       const float w = wm[(size_t)k * 3072];
; #pragma unroll
;       for (int r = 0; r < 24; ++r) {
;         const float c = r < 8 ? p.c_prompt[r * 1024 + k] : p.c_sample[(r - 8) * 1024 + k];
;         acc[r] = fmaf(siluf_(c), w, acc[r]);
;       }
;     }
;     __syncthreads();
; #pragma unroll
;     for (int r = 0; r < 24; ++r) red[(ks * 24 + r) * 32 + col] = acc[r];
;     __syncthreads();
;     for (int o = tidx(); o < 768; o += 256) {
;       const int r = o >> 5, c = o & 31;
;       float s = p.b_mod[l * 3072 + cg_ * 32 + c];
; #pragma unroll
;       for (int k8 = 0; k8 < 8; ++k8) s += red[(k8 * 24 + r) * 32 + c];
;       ((float*)(p.ws + WS_mod))[((size_t)l * 24 + r) * 3072 + cg_ * 32 + c] = s;
;     }
	v_fmac_f32_dpp v31, v80, v84 row_newbcast:7 row_mask:0xf bank_mask:0xf
	v_fmac_f32_dpp v60, v77, v85 row_newbcast:0 row_mask:0xf bank_mask:0xf
	v_fmac_f32_dpp v61, v77, v85 row_newbcast:1 row_mask:0xf bank_mask:0xf
	v_fmac_f32_dpp v58, v77, v85 row_newbcast:2 row_mask:0xf bank_mask:0xf
	v_fmac_f32_dpp v59, v77, v85 row_newbcast:3 row_mask:0xf bank_mask:0xf
	v_fmac_f32_dpp v56, v77, v85 row_newbcast:4 row_mask:0xf bank_mask:0xf
	v_fmac_f32_dpp v57, v77, v85 row_newbcast:5 row_mask:0xf bank_mask:0xf
	v_fmac_f32_dpp v54, v77, v85 row_newbcast:6 row_mask:0xf bank_mask:0xf
	v_fmac_f32_dpp v55, v77, v85 row_newbcast:7 row_mask:0xf bank_mask:0xf
	v_fmac_f32_dpp v52, v77, v85 row_newbcast:8 row_mask:0xf bank_mask:0xf
	v_fmac_f32_dpp v53, v77, v85 row_newbcast:9 row_mask:0xf bank_mask:0xf
	v_fmac_f32_dpp v50, v77, v85 row_newbcast:10 row_mask:0xf bank_mask:0xf
	v_fmac_f32_dpp v51, v77, v85 row_newbcast:11 row_mask:0xf bank_mask:0xf
	v_fmac_f32_dpp v46, v77, v85 row_newbcast:12 row_mask:0xf bank_mask:0xf
	v_fmac_f32_dpp v47, v77, v85 row_newbcast:13 row_mask:0xf bank_mask:0xf
	v_fmac_f32_dpp v44, v77, v85 row_newbcast:14 row_mask:0xf bank_mask:0xf
	v_fmac_f32_dpp v45, v77, v85 row_newbcast:15 row_mask:0xf bank_mask:0xf
	v_fmac_f32_dpp v42, v81, v85 row_newbcast:0 row_mask:0xf bank_mask:0xf
	v_fmac_f32_dpp v43, v81, v85 row_newbcast:1 row_mask:0xf bank_mask:0xf
	v_fmac_f32_dpp v40, v81, v85 row_newbcast:2 row_mask:0xf bank_mask:0xf
	v_fmac_f32_dpp v41, v81, v85 row_newbcast:3 row_mask:0xf bank_mask:0xf
	v_fmac_f32_dpp v34, v81, v85 row_newbcast:4 row_mask:0xf bank_mask:0xf
	v_fmac_f32_dpp v35, v81, v85 row_newbcast:5 row_mask:0xf bank_mask:0xf
	v_fmac_f32_dpp v30, v81, v85 row_newbcast:6 row_mask:0xf bank_mask:0xf
	v_fmac_f32_dpp v31, v81, v85 row_newbcast:7 row_mask:0xf bank_mask:0xf
	v_fmac_f32_dpp v60, v78, v86 row_newbcast:0 row_mask:0xf bank_mask:0xf
	v_fmac_f32_dpp v61, v78, v86 row_newbcast:1 row_mask:0xf bank_mask:0xf
	v_fmac_f32_dpp v58, v78, v86 row_newbcast:2 row_mask:0xf bank_mask:0xf
	v_fmac_f32_dpp v59, v78, v86 row_newbcast:3 row_mask:0xf bank_mask:0xf
	v_fmac_f32_dpp v56, v78, v86 row_newbcast:4 row_mask:0xf bank_mask:0xf
	v_fmac_f32_dpp v57, v78, v86 row_newbcast:5 row_mask:0xf bank_mask:0xf
	v_fmac_f32_dpp v54, v78, v86 row_newbcast:6 row_mask:0xf bank_mask:0xf
	v_fmac_f32_dpp v55, v78, v86 row_newbcast:7 row_mask:0xf bank_mask:0xf
	v_fmac_f32_dpp v52, v78, v86 row_newbcast:8 row_mask:0xf bank_mask:0xf
	v_fmac_f32_dpp v53, v78, v86 row_newbcast:9 row_mask:0xf bank_mask:0xf
	v_fmac_f32_dpp v50, v78, v86 row_newbcast:10 row_mask:0xf bank_mask:0xf
	v_fmac_f32_dpp v51, v78, v86 row_newbcast:11 row_mask:0xf bank_mask:0xf
	v_fmac_f32_dpp v46, v78, v86 row_newbcast:12 row_mask:0xf bank_mask:0xf
	v_fmac_f32_dpp v47, v78, v86 row_newbcast:13 row_mask:0xf bank_mask:0xf
	v_fmac_f32_dpp v44, v78, v86 row_newbcast:14 row_mask:0xf bank_mask:0xf
	v_fmac_f32_dpp v45, v78, v86 row_newbcast:15 row_mask:0xf bank_mask:0xf
	v_fmac_f32_dpp v42, v82, v86 row_newbcast:0 row_mask:0xf bank_mask:0xf
	v_fmac_f32_dpp v43, v82, v86 row_newbcast:1 row_mask:0xf bank_mask:0xf
	v_fmac_f32_dpp v40, v82, v86 row_newbcast:2 row_mask:0xf bank_mask:0xf
	v_fmac_f32_dpp v41, v82, v86 row_newbcast:3 row_mask:0xf bank_mask:0xf
	v_fmac_f32_dpp v34, v82, v86 row_newbcast:4 row_mask:0xf bank_mask:0xf
	v_fmac_f32_dpp v35, v82, v86 row_newbcast:5 row_mask:0xf bank_mask:0xf
	v_fmac_f32_dpp v30, v82, v86 row_newbcast:6 row_mask:0xf bank_mask:0xf
	v_fmac_f32_dpp v31, v82, v86 row_newbcast:7 row_mask:0xf bank_mask:0xf
	v_fmac_f32_dpp v60, v79, v87 row_newbcast:0 row_mask:0xf bank_mask:0xf
	v_fmac_f32_dpp v61, v79, v87 row_newbcast:1 row_mask:0xf bank_mask:0xf
	v_fmac_f32_dpp v58, v79, v87 row_newbcast:2 row_mask:0xf bank_mask:0xf
	v_fmac_f32_dpp v59, v79, v87 row_newbcast:3 row_mask:0xf bank_mask:0xf
	v_fmac_f32_dpp v56, v79, v87 row_newbcast:4 row_mask:0xf bank_mask:0xf
	v_fmac_f32_dpp v57, v79, v87 row_newbcast:5 row_mask:0xf bank_mask:0xf
	v_fmac_f32_dpp v54, v79, v87 row_newbcast:6 row_mask:0xf bank_mask:0xf
	v_fmac_f32_dpp v55, v79, v87 row_newbcast:7 row_mask:0xf bank_mask:0xf
	v_fmac_f32_dpp v52, v79, v87 row_newbcast:8 row_mask:0xf bank_mask:0xf
	v_fmac_f32_dpp v53, v79, v87 row_newbcast:9 row_mask:0xf bank_mask:0xf
	v_fmac_f32_dpp v50, v79, v87 row_newbcast:10 row_mask:0xf bank_mask:0xf
	v_fmac_f32_dpp v51, v79, v87 row_newbcast:11 row_mask:0xf bank_mask:0xf
	v_fmac_f32_dpp v46, v79, v87 row_newbcast:12 row_mask:0xf bank_mask:0xf
	v_fmac_f32_dpp v47, v79, v87 row_newbcast:13 row_mask:0xf bank_mask:0xf
	v_fmac_f32_dpp v44, v79, v87 row_newbcast:14 row_mask:0xf bank_mask:0xf
	v_fmac_f32_dpp v45, v79, v87 row_newbcast:15 row_mask:0xf bank_mask:0xf
	v_fmac_f32_dpp v42, v83, v87 row_newbcast:0 row_mask:0xf bank_mask:0xf
	v_fmac_f32_dpp v43, v83, v87 row_newbcast:1 row_mask:0xf bank_mask:0xf
	v_fmac_f32_dpp v40, v83, v87 row_newbcast:2 row_mask:0xf bank_mask:0xf
	v_fmac_f32_dpp v41, v83, v87 row_newbcast:3 row_mask:0xf bank_mask:0xf
	v_fmac_f32_dpp v34, v83, v87 row_newbcast:4 row_mask:0xf bank_mask:0xf
	v_fmac_f32_dpp v35, v83, v87 row_newbcast:5 row_mask:0xf bank_mask:0xf
	v_fmac_f32_dpp v30, v83, v87 row_newbcast:6 row_mask:0xf bank_mask:0xf
	v_fmac_f32_dpp v31, v83, v87 row_newbcast:7 row_mask:0xf bank_mask:0xf
	s_cmpk_eq_i32 s4, 0x200
	s_cbranch_scc0 .Lmod_kloop
	s_mov_b64 s[10:11], 0x3000
	s_movk_i32 s1, 0xc00
	v_lshlrev_b32_e32 v0, 2, v63
	v_mul_lo_u32 v2, v62, s1
	v_add3_u32 v0, 0, v0, v2
	s_barrier
	ds_write2_b32 v0, v61, v60 offset1:32
	ds_write2_b32 v0, v59, v58 offset0:64 offset1:96
	ds_write2_b32 v0, v57, v56 offset0:128 offset1:160
	ds_write2_b32 v0, v55, v54 offset0:192 offset1:224
	v_add_u32_e32 v2, 0x400, v0
	v_add_u32_e32 v0, 0x800, v0
	v_mov_b32_e32 v6, v154
	s_movk_i32 s1, 0x300
	ds_write2_b32 v2, v53, v52 offset1:32
	ds_write2_b32 v2, v51, v50 offset0:64 offset1:96
	ds_write2_b32 v2, v47, v46 offset0:128 offset1:160
	ds_write2_b32 v2, v45, v44 offset0:192 offset1:224
	ds_write2_b32 v0, v43, v42 offset1:32
	ds_write2_b32 v0, v41, v40 offset0:64 offset1:96
	ds_write2_b32 v0, v35, v34 offset0:128 offset1:160
	ds_write2_b32 v0, v31, v30 offset0:192 offset1:224
	s_waitcnt lgkmcnt(0)
	s_barrier
	s_nop 0
	v_cmp_gt_i32_e32 vcc, s1, v6
	s_and_saveexec_b64 s[4:5], vcc
	s_cbranch_execz .LBB0_1589
	s_mul_i32 s1, s9, 0xc00
	s_add_i32 s10, s1, s0
	v_and_b32_e32 v0, 31, v6
	s_add_u32 s2, s6, s2
	v_or_b32_e32 v2, s10, v0
	s_addc_u32 s3, s7, s3
	v_ashrrev_i32_e32 v3, 31, v2
	v_lshlrev_b32_e32 v0, 2, v0
	s_mul_hi_i32 s1, s9, 24
	s_mul_i32 s0, s9, 24
	v_lshl_add_u64 v[2:3], v[2:3], 2, s[20:21]
	v_add_u32_e32 v7, 0, v0
	v_lshl_add_u64 v[4:5], s[2:3], 0, v[0:1]
	s_mov_b64 s[2:3], 0
